# v41 + un-aligned epilogues for units with a successor (leading half skips its align barrier, trailing half's re-stagger barrier removed), P1..P7
# baseline (speedup 1.0000x reference)
; __device__ __forceinline__ unsigned cvt_pk_bf16(float lo, float hi) { unsigned r; asm volatile("v_cvt_pk_bf16_f32 %0, %1, %2" : "=v"(r) : "v"(lo), "v"(hi)); return r; }
; #define PG8_BAR __builtin_amdgcn_s_barrier()
;     __device__ __forceinline__ void operator()(f32x4 (&acc)[2][2][4][2], const Unit& u, int wr, int wc, int fr, int fq) const {
;         const int row0 = u.pm * BM + wr * 64 + fr, col0 = u.pn * HALF + wc * 32 + 8 * fq;
;         bf16_t* Ob = O + ((size_t)(u.pm * ldc + (col0 >> 6)) * BM) * 64;
;         float sq[2][4];
; #pragma unroll
;         for (int ai = 0; ai < 2; ++ai)
; #pragma unroll
;             for (int m = 0; m < 4; ++m) sq[ai][m] = ssq[row0 + ai * HALF + m * 16];
; #pragma unroll
;         for (int ai = 0; ai < 2; ++ai)
; #pragma unroll
;             for (int m = 0; m < 4; ++m) { const float ms = sq[ai][m] * (1.0f / 1024.0f) + 1e-6f, nrl = -__builtin_amdgcn_rsqf(ms) * LOG2E;
;                 float o[8];
; #pragma unroll
;                 for (int n = 0; n < 2; ++n)
; #pragma unroll
;                     for (int e = 0; e < 4; ++e) { const float a = acc[ai][0][m][n][e], bb = acc[ai][1][m][n][e];
;                         o[4 * n + e] = (a * bb) * __builtin_amdgcn_rcpf(__builtin_fmaf(__builtin_amdgcn_exp2f(a * nrl), ms, ms)); }
;                 u32x4 w; w.x = cvt_pk_bf16(o[0], o[1]); w.y = cvt_pk_bf16(o[2], o[3]); w.z = cvt_pk_bf16(o[4], o[5]); w.w = cvt_pk_bf16(o[6], o[7]);
;                 *(u32x4*)((char*)Ob + ai * HTB + lds_byte(wr * 64 + m * 16 + fr, (col0 & 63))) = w; }
; template <class Epi, class Sched, bool ALIGN_EPI = false, bool SP2 = false>
; __device__ __forceinline__ void gemm_phase(PG8_LAS unsigned char* lds, const Gemm g, const Sched& S, const Epi& E) {
;     ...
;         if constexpr (ALIGN_EPI) { if (wr == 0) PG8_BAR; }
.LBB0_144:
	v_lshl_add_u32 v150, s68, 8, v142
	v_ashrrev_i32_e32 v151, 31, v150
	v_lshl_add_u64 v[150:151], v[150:151], 2, s[22:23]
	global_load_dword v149, v[150:151], off
	global_load_dword v152, v[150:151], off offset:64
	global_load_dword v156, v[150:151], off offset:128
	global_load_dword v157, v[150:151], off offset:192
	global_load_dword v158, v[150:151], off offset:512
	global_load_dword v159, v[150:151], off offset:576
	global_load_dword v160, v[150:151], off offset:640
	global_load_dword v178, v[150:151], off offset:704
	s_lshl_b32 s8, s69, 7
	s_or_b32 s8, s8, s79
	s_mul_i32 s9, s68, 44
	s_ashr_i32 s8, s8, 6
	s_add_i32 s8, s8, s9
	s_ashr_i32 s9, s8, 31
	s_lshl_b64 s[8:9], s[8:9], 15
	s_add_u32 s68, s28, s8
	s_addc_u32 s69, s29, s9
	v_pk_mul_f32 v[124:125], v[116:117], v[124:125]
	v_pk_mul_f32 v[126:127], v[118:119], v[126:127]
	v_pk_mul_f32 v[120:121], v[112:113], v[120:121]
	v_pk_mul_f32 v[122:123], v[114:115], v[122:123]
	v_pk_mul_f32 v[104:105], v[108:109], v[104:105]
	v_pk_mul_f32 v[106:107], v[110:111], v[106:107]
	v_pk_mul_f32 v[96:97], v[100:101], v[96:97]
	v_pk_mul_f32 v[98:99], v[102:103], v[98:99]
	v_pk_mul_f32 v[88:89], v[92:93], v[88:89]
	v_pk_mul_f32 v[90:91], v[94:95], v[90:91]
	v_pk_mul_f32 v[80:81], v[84:85], v[80:81]
	v_pk_mul_f32 v[82:83], v[86:87], v[82:83]
	v_pk_mul_f32 v[72:73], v[76:77], v[72:73]
	v_pk_mul_f32 v[74:75], v[78:79], v[74:75]
	v_pk_mul_f32 v[64:65], v[68:69], v[64:65]
	v_pk_mul_f32 v[66:67], v[70:71], v[66:67]
	v_pk_mul_f32 v[56:57], v[60:61], v[56:57]
	v_pk_mul_f32 v[58:59], v[62:63], v[58:59]
	v_pk_mul_f32 v[48:49], v[52:53], v[48:49]
	v_pk_mul_f32 v[50:51], v[54:55], v[50:51]
	v_pk_mul_f32 v[40:41], v[44:45], v[40:41]
	v_pk_mul_f32 v[42:43], v[46:47], v[42:43]
	v_pk_mul_f32 v[32:33], v[36:37], v[32:33]
	v_pk_mul_f32 v[34:35], v[38:39], v[34:35]
	v_pk_mul_f32 v[24:25], v[28:29], v[24:25]
	v_pk_mul_f32 v[26:27], v[30:31], v[26:27]
	v_pk_mul_f32 v[16:17], v[20:21], v[16:17]
	v_pk_mul_f32 v[18:19], v[22:23], v[18:19]
	v_pk_mul_f32 v[8:9], v[12:13], v[8:9]
	v_pk_mul_f32 v[10:11], v[14:15], v[10:11]
	v_pk_mul_f32 v[0:1], v[4:5], v[0:1]
	v_pk_mul_f32 v[2:3], v[6:7], v[2:3]
	s_cmp_lg_u64 s[2:3], 0
	s_cbranch_scc1 .Lnoal_0
	v_readlane_b32 s99, v246, 6
	s_nop 1
	s_cmp_lt_u32 s99, 4
	s_cbranch_scc0 .Lnoal_0
	s_barrier
.Lnoal_0:
	s_waitcnt vmcnt(0)
	v_fmamk_f32 v154, v149, 0x3a800000, v148
	v_fmamk_f32 v162, v152, 0x3a800000, v148
	v_fmamk_f32 v164, v156, 0x3a800000, v148
	v_fmamk_f32 v166, v157, 0x3a800000, v148
	v_fmamk_f32 v168, v158, 0x3a800000, v148
	v_fmamk_f32 v170, v159, 0x3a800000, v148
	v_fmamk_f32 v172, v160, 0x3a800000, v148
	v_fmamk_f32 v174, v178, 0x3a800000, v148
	v_rsq_f32_e32 v155, v154
	v_rsq_f32_e32 v163, v162
	v_rsq_f32_e32 v165, v164
	v_rsq_f32_e32 v167, v166
	v_rsq_f32_e32 v169, v168
	v_rsq_f32_e32 v171, v170
	v_rsq_f32_e32 v173, v172
	v_rsq_f32_e32 v175, v174
	v_mul_f32_e32 v155, 0xbfb8aa3b, v155
	v_mul_f32_e32 v163, 0xbfb8aa3b, v163
	v_mul_f32_e32 v165, 0xbfb8aa3b, v165
	v_mul_f32_e32 v167, 0xbfb8aa3b, v167
	v_mul_f32_e32 v169, 0xbfb8aa3b, v169
	v_mul_f32_e32 v171, 0xbfb8aa3b, v171
	v_mul_f32_e32 v173, 0xbfb8aa3b, v173
	v_mul_f32_e32 v175, 0xbfb8aa3b, v175
	v_pk_mul_f32 v[116:117], v[116:117], v[154:155] op_sel:[0,1] op_sel_hi:[1,1]
	v_pk_mul_f32 v[118:119], v[118:119], v[154:155] op_sel:[0,1] op_sel_hi:[1,1]
	v_pk_mul_f32 v[112:113], v[112:113], v[154:155] op_sel:[0,1] op_sel_hi:[1,1]
	v_pk_mul_f32 v[114:115], v[114:115], v[154:155] op_sel:[0,1] op_sel_hi:[1,1]
	v_exp_f32_e32 v116, v116
	v_exp_f32_e32 v117, v117
	v_exp_f32_e32 v118, v118
	v_exp_f32_e32 v119, v119
	v_exp_f32_e32 v112, v112
	v_exp_f32_e32 v113, v113
	v_exp_f32_e32 v114, v114
	v_exp_f32_e32 v115, v115
	v_pk_fma_f32 v[116:117], v[116:117], v[154:155], v[154:155] op_sel_hi:[1,0,0]
	v_pk_fma_f32 v[118:119], v[118:119], v[154:155], v[154:155] op_sel_hi:[1,0,0]
	v_pk_fma_f32 v[112:113], v[112:113], v[154:155], v[154:155] op_sel_hi:[1,0,0]
	v_pk_fma_f32 v[114:115], v[114:115], v[154:155], v[154:155] op_sel_hi:[1,0,0]
	v_rcp_f32_e32 v116, v116
	v_rcp_f32_e32 v117, v117
	v_rcp_f32_e32 v118, v118
	v_rcp_f32_e32 v119, v119
	v_rcp_f32_e32 v112, v112
	v_rcp_f32_e32 v113, v113
	v_rcp_f32_e32 v114, v114
	v_rcp_f32_e32 v115, v115
	v_pk_mul_f32 v[124:125], v[124:125], v[116:117]
	v_pk_mul_f32 v[126:127], v[126:127], v[118:119]
	v_pk_mul_f32 v[120:121], v[120:121], v[112:113]
	v_pk_mul_f32 v[122:123], v[122:123], v[114:115]
	v_cvt_pk_bf16_f32 v208, v124, v125
	v_cvt_pk_bf16_f32 v209, v126, v127
	v_cvt_pk_bf16_f32 v210, v120, v121
	v_cvt_pk_bf16_f32 v211, v122, v123
	v_lshl_add_u64 v[176:177], s[68:69], 0, v[130:131]
	global_store_dwordx4 v[176:177], v[208:211], off sc1
	v_pk_mul_f32 v[108:109], v[108:109], v[162:163] op_sel:[0,1] op_sel_hi:[1,1]
	v_pk_mul_f32 v[110:111], v[110:111], v[162:163] op_sel:[0,1] op_sel_hi:[1,1]
	v_pk_mul_f32 v[100:101], v[100:101], v[162:163] op_sel:[0,1] op_sel_hi:[1,1]
	v_pk_mul_f32 v[102:103], v[102:103], v[162:163] op_sel:[0,1] op_sel_hi:[1,1]
	v_exp_f32_e32 v108, v108
	v_exp_f32_e32 v109, v109
	v_exp_f32_e32 v110, v110
	v_exp_f32_e32 v111, v111
	v_exp_f32_e32 v100, v100
	v_exp_f32_e32 v101, v101
	v_exp_f32_e32 v102, v102
	v_exp_f32_e32 v103, v103
	v_pk_fma_f32 v[108:109], v[108:109], v[162:163], v[162:163] op_sel_hi:[1,0,0]
	v_pk_fma_f32 v[110:111], v[110:111], v[162:163], v[162:163] op_sel_hi:[1,0,0]
	v_pk_fma_f32 v[100:101], v[100:101], v[162:163], v[162:163] op_sel_hi:[1,0,0]
	v_pk_fma_f32 v[102:103], v[102:103], v[162:163], v[162:163] op_sel_hi:[1,0,0]
	v_rcp_f32_e32 v108, v108
	v_rcp_f32_e32 v109, v109
	v_rcp_f32_e32 v110, v110
	v_rcp_f32_e32 v111, v111
	v_rcp_f32_e32 v100, v100
; __device__ __forceinline__ unsigned cvt_pk_bf16(float lo, float hi) { unsigned r; asm volatile("v_cvt_pk_bf16_f32 %0, %1, %2" : "=v"(r) : "v"(lo), "v"(hi)); return r; }
;     __device__ __forceinline__ void operator()(f32x4 (&acc)[2][2][4][2], const Unit& u, int wr, int wc, int fr, int fq) const {
;     ...
;         for (int ai = 0; ai < 2; ++ai)
; #pragma unroll
;             for (int m = 0; m < 4; ++m) { const float ms = sq[ai][m] * (1.0f / 1024.0f) + 1e-6f, nrl = -__builtin_amdgcn_rsqf(ms) * LOG2E;
;                 float o[8];
; #pragma unroll
;                 for (int n = 0; n < 2; ++n)
; #pragma unroll
;                     for (int e = 0; e < 4; ++e) { const float a = acc[ai][0][m][n][e], bb = acc[ai][1][m][n][e];
;                         o[4 * n + e] = (a * bb) * __builtin_amdgcn_rcpf(__builtin_fmaf(__builtin_amdgcn_exp2f(a * nrl), ms, ms)); }
;                 u32x4 w; w.x = cvt_pk_bf16(o[0], o[1]); w.y = cvt_pk_bf16(o[2], o[3]); w.z = cvt_pk_bf16(o[4], o[5]); w.w = cvt_pk_bf16(o[6], o[7]);
;                 *(u32x4*)((char*)Ob + ai * HTB + lds_byte(wr * 64 + m * 16 + fr, (col0 & 63))) = w; }
	v_rcp_f32_e32 v101, v101
	v_rcp_f32_e32 v102, v102
	v_rcp_f32_e32 v103, v103
	v_pk_mul_f32 v[104:105], v[104:105], v[108:109]
	v_pk_mul_f32 v[106:107], v[106:107], v[110:111]
	v_pk_mul_f32 v[96:97], v[96:97], v[100:101]
	v_pk_mul_f32 v[98:99], v[98:99], v[102:103]
	v_cvt_pk_bf16_f32 v212, v104, v105
	v_cvt_pk_bf16_f32 v213, v106, v107
	v_cvt_pk_bf16_f32 v214, v96, v97
	v_cvt_pk_bf16_f32 v215, v98, v99
	v_lshl_add_u64 v[176:177], s[68:69], 0, v[132:133]
	global_store_dwordx4 v[176:177], v[212:215], off sc1
	v_pk_mul_f32 v[92:93], v[92:93], v[164:165] op_sel:[0,1] op_sel_hi:[1,1]
	v_pk_mul_f32 v[94:95], v[94:95], v[164:165] op_sel:[0,1] op_sel_hi:[1,1]
	v_pk_mul_f32 v[84:85], v[84:85], v[164:165] op_sel:[0,1] op_sel_hi:[1,1]
	v_pk_mul_f32 v[86:87], v[86:87], v[164:165] op_sel:[0,1] op_sel_hi:[1,1]
	v_exp_f32_e32 v92, v92
	v_exp_f32_e32 v93, v93
	v_exp_f32_e32 v94, v94
	v_exp_f32_e32 v95, v95
	v_exp_f32_e32 v84, v84
	v_exp_f32_e32 v85, v85
	v_exp_f32_e32 v86, v86
	v_exp_f32_e32 v87, v87
	v_pk_fma_f32 v[92:93], v[92:93], v[164:165], v[164:165] op_sel_hi:[1,0,0]
	v_pk_fma_f32 v[94:95], v[94:95], v[164:165], v[164:165] op_sel_hi:[1,0,0]
	v_pk_fma_f32 v[84:85], v[84:85], v[164:165], v[164:165] op_sel_hi:[1,0,0]
	v_pk_fma_f32 v[86:87], v[86:87], v[164:165], v[164:165] op_sel_hi:[1,0,0]
	v_rcp_f32_e32 v92, v92
	v_rcp_f32_e32 v93, v93
	v_rcp_f32_e32 v94, v94
	v_rcp_f32_e32 v95, v95
	v_rcp_f32_e32 v84, v84
	v_rcp_f32_e32 v85, v85
	v_rcp_f32_e32 v86, v86
	v_rcp_f32_e32 v87, v87
	v_pk_mul_f32 v[88:89], v[88:89], v[92:93]
	v_pk_mul_f32 v[90:91], v[90:91], v[94:95]
	v_pk_mul_f32 v[80:81], v[80:81], v[84:85]
	v_pk_mul_f32 v[82:83], v[82:83], v[86:87]
	v_cvt_pk_bf16_f32 v208, v88, v89
	v_cvt_pk_bf16_f32 v209, v90, v91
	v_cvt_pk_bf16_f32 v210, v80, v81
	v_cvt_pk_bf16_f32 v211, v82, v83
	v_lshl_add_u64 v[176:177], s[68:69], 0, v[134:135]
	global_store_dwordx4 v[176:177], v[208:211], off sc1
	v_pk_mul_f32 v[76:77], v[76:77], v[166:167] op_sel:[0,1] op_sel_hi:[1,1]
	v_pk_mul_f32 v[78:79], v[78:79], v[166:167] op_sel:[0,1] op_sel_hi:[1,1]
	v_pk_mul_f32 v[68:69], v[68:69], v[166:167] op_sel:[0,1] op_sel_hi:[1,1]
	v_pk_mul_f32 v[70:71], v[70:71], v[166:167] op_sel:[0,1] op_sel_hi:[1,1]
	v_exp_f32_e32 v76, v76
	v_exp_f32_e32 v77, v77
	v_exp_f32_e32 v78, v78
	v_exp_f32_e32 v79, v79
	v_exp_f32_e32 v68, v68
	v_exp_f32_e32 v69, v69
	v_exp_f32_e32 v70, v70
	v_exp_f32_e32 v71, v71
	v_pk_fma_f32 v[76:77], v[76:77], v[166:167], v[166:167] op_sel_hi:[1,0,0]
	v_pk_fma_f32 v[78:79], v[78:79], v[166:167], v[166:167] op_sel_hi:[1,0,0]
	v_pk_fma_f32 v[68:69], v[68:69], v[166:167], v[166:167] op_sel_hi:[1,0,0]
	v_pk_fma_f32 v[70:71], v[70:71], v[166:167], v[166:167] op_sel_hi:[1,0,0]
	v_rcp_f32_e32 v76, v76
	v_rcp_f32_e32 v77, v77
	v_rcp_f32_e32 v78, v78
	v_rcp_f32_e32 v79, v79
	v_rcp_f32_e32 v68, v68
	v_rcp_f32_e32 v69, v69
	v_rcp_f32_e32 v70, v70
	v_rcp_f32_e32 v71, v71
	v_pk_mul_f32 v[72:73], v[72:73], v[76:77]
	v_pk_mul_f32 v[74:75], v[74:75], v[78:79]
	v_pk_mul_f32 v[64:65], v[64:65], v[68:69]
	v_pk_mul_f32 v[66:67], v[66:67], v[70:71]
	v_cvt_pk_bf16_f32 v212, v72, v73
	v_cvt_pk_bf16_f32 v213, v74, v75
	v_cvt_pk_bf16_f32 v214, v64, v65
	v_cvt_pk_bf16_f32 v215, v66, v67
	v_lshl_add_u64 v[176:177], s[68:69], 0, v[136:137]
	global_store_dwordx4 v[176:177], v[212:215], off sc1
	s_add_u32 s68, s68, 0x4000
	s_addc_u32 s69, s69, 0
	v_pk_mul_f32 v[60:61], v[60:61], v[168:169] op_sel:[0,1] op_sel_hi:[1,1]
	v_pk_mul_f32 v[62:63], v[62:63], v[168:169] op_sel:[0,1] op_sel_hi:[1,1]
	v_pk_mul_f32 v[52:53], v[52:53], v[168:169] op_sel:[0,1] op_sel_hi:[1,1]
	v_pk_mul_f32 v[54:55], v[54:55], v[168:169] op_sel:[0,1] op_sel_hi:[1,1]
	v_exp_f32_e32 v60, v60
	v_exp_f32_e32 v61, v61
	v_exp_f32_e32 v62, v62
	v_exp_f32_e32 v63, v63
	v_exp_f32_e32 v52, v52
	v_exp_f32_e32 v53, v53
	v_exp_f32_e32 v54, v54
	v_exp_f32_e32 v55, v55
	v_pk_fma_f32 v[60:61], v[60:61], v[168:169], v[168:169] op_sel_hi:[1,0,0]
	v_pk_fma_f32 v[62:63], v[62:63], v[168:169], v[168:169] op_sel_hi:[1,0,0]
	v_pk_fma_f32 v[52:53], v[52:53], v[168:169], v[168:169] op_sel_hi:[1,0,0]
	v_pk_fma_f32 v[54:55], v[54:55], v[168:169], v[168:169] op_sel_hi:[1,0,0]
	v_rcp_f32_e32 v60, v60
	v_rcp_f32_e32 v61, v61
	v_rcp_f32_e32 v62, v62
	v_rcp_f32_e32 v63, v63
	v_rcp_f32_e32 v52, v52
	v_rcp_f32_e32 v53, v53
	v_rcp_f32_e32 v54, v54
	v_rcp_f32_e32 v55, v55
	v_pk_mul_f32 v[56:57], v[56:57], v[60:61]
	v_pk_mul_f32 v[58:59], v[58:59], v[62:63]
	v_pk_mul_f32 v[48:49], v[48:49], v[52:53]
	v_pk_mul_f32 v[50:51], v[50:51], v[54:55]
; __device__ __forceinline__ unsigned cvt_pk_bf16(float lo, float hi) { unsigned r; asm volatile("v_cvt_pk_bf16_f32 %0, %1, %2" : "=v"(r) : "v"(lo), "v"(hi)); return r; }
; #define PG8_BAR __builtin_amdgcn_s_barrier()
;     __device__ __forceinline__ void operator()(f32x4 (&acc)[2][2][4][2], const Unit& u, int wr, int wc, int fr, int fq) const {
;     ...
;         for (int ai = 0; ai < 2; ++ai)
; #pragma unroll
;             for (int m = 0; m < 4; ++m) { const float ms = sq[ai][m] * (1.0f / 1024.0f) + 1e-6f, nrl = -__builtin_amdgcn_rsqf(ms) * LOG2E;
;                 float o[8];
; #pragma unroll
;                 for (int n = 0; n < 2; ++n)
; #pragma unroll
;                     for (int e = 0; e < 4; ++e) { const float a = acc[ai][0][m][n][e], bb = acc[ai][1][m][n][e];
;                         o[4 * n + e] = (a * bb) * __builtin_amdgcn_rcpf(__builtin_fmaf(__builtin_amdgcn_exp2f(a * nrl), ms, ms)); }
;                 u32x4 w; w.x = cvt_pk_bf16(o[0], o[1]); w.y = cvt_pk_bf16(o[2], o[3]); w.z = cvt_pk_bf16(o[4], o[5]); w.w = cvt_pk_bf16(o[6], o[7]);
;                 *(u32x4*)((char*)Ob + ai * HTB + lds_byte(wr * 64 + m * 16 + fr, (col0 & 63))) = w; }
; template <class Epi, class Sched, bool ALIGN_EPI = false, bool SP2 = false>
; __device__ __forceinline__ void gemm_phase(PG8_LAS unsigned char* lds, const Gemm g, const Sched& S, const Epi& E) {
;     ...
;         if (!has_next) break;
; #pragma unroll
;         for (int a = 0; a < 2; ++a)
; #pragma unroll
;             for (int b = 0; b < 2; ++b)
; #pragma unroll
;                 for (int m = 0; m < 4; ++m)
; #pragma unroll
;                     for (int n = 0; n < 2; ++n) acc[a][b][m][n] = (f32x4){0.f, 0.f, 0.f, 0.f};
;         cur = nxt; cA = nA; cB = nB; ++ui;
;         if constexpr (ALIGN_EPI) { if (wr == 1) PG8_BAR; }
	v_cvt_pk_bf16_f32 v208, v56, v57
	v_cvt_pk_bf16_f32 v209, v58, v59
	v_cvt_pk_bf16_f32 v210, v48, v49
	v_cvt_pk_bf16_f32 v211, v50, v51
	v_lshl_add_u64 v[176:177], s[68:69], 0, v[130:131]
	global_store_dwordx4 v[176:177], v[208:211], off sc1
	v_pk_mul_f32 v[44:45], v[44:45], v[170:171] op_sel:[0,1] op_sel_hi:[1,1]
	v_pk_mul_f32 v[46:47], v[46:47], v[170:171] op_sel:[0,1] op_sel_hi:[1,1]
	v_pk_mul_f32 v[36:37], v[36:37], v[170:171] op_sel:[0,1] op_sel_hi:[1,1]
	v_pk_mul_f32 v[38:39], v[38:39], v[170:171] op_sel:[0,1] op_sel_hi:[1,1]
	v_exp_f32_e32 v44, v44
	v_exp_f32_e32 v45, v45
	v_exp_f32_e32 v46, v46
	v_exp_f32_e32 v47, v47
	v_exp_f32_e32 v36, v36
	v_exp_f32_e32 v37, v37
	v_exp_f32_e32 v38, v38
	v_exp_f32_e32 v39, v39
	v_pk_fma_f32 v[44:45], v[44:45], v[170:171], v[170:171] op_sel_hi:[1,0,0]
	v_pk_fma_f32 v[46:47], v[46:47], v[170:171], v[170:171] op_sel_hi:[1,0,0]
	v_pk_fma_f32 v[36:37], v[36:37], v[170:171], v[170:171] op_sel_hi:[1,0,0]
	v_pk_fma_f32 v[38:39], v[38:39], v[170:171], v[170:171] op_sel_hi:[1,0,0]
	v_rcp_f32_e32 v44, v44
	v_rcp_f32_e32 v45, v45
	v_rcp_f32_e32 v46, v46
	v_rcp_f32_e32 v47, v47
	v_rcp_f32_e32 v36, v36
	v_rcp_f32_e32 v37, v37
	v_rcp_f32_e32 v38, v38
	v_rcp_f32_e32 v39, v39
	v_pk_mul_f32 v[40:41], v[40:41], v[44:45]
	v_pk_mul_f32 v[42:43], v[42:43], v[46:47]
	v_pk_mul_f32 v[32:33], v[32:33], v[36:37]
	v_pk_mul_f32 v[34:35], v[34:35], v[38:39]
	v_cvt_pk_bf16_f32 v212, v40, v41
	v_cvt_pk_bf16_f32 v213, v42, v43
	v_cvt_pk_bf16_f32 v214, v32, v33
	v_cvt_pk_bf16_f32 v215, v34, v35
	v_lshl_add_u64 v[176:177], s[68:69], 0, v[132:133]
	global_store_dwordx4 v[176:177], v[212:215], off sc1
	v_pk_mul_f32 v[28:29], v[28:29], v[172:173] op_sel:[0,1] op_sel_hi:[1,1]
	v_pk_mul_f32 v[30:31], v[30:31], v[172:173] op_sel:[0,1] op_sel_hi:[1,1]
	v_pk_mul_f32 v[20:21], v[20:21], v[172:173] op_sel:[0,1] op_sel_hi:[1,1]
	v_pk_mul_f32 v[22:23], v[22:23], v[172:173] op_sel:[0,1] op_sel_hi:[1,1]
	v_exp_f32_e32 v28, v28
	v_exp_f32_e32 v29, v29
	v_exp_f32_e32 v30, v30
	v_exp_f32_e32 v31, v31
	v_exp_f32_e32 v20, v20
	v_exp_f32_e32 v21, v21
	v_exp_f32_e32 v22, v22
	v_exp_f32_e32 v23, v23
	v_pk_fma_f32 v[28:29], v[28:29], v[172:173], v[172:173] op_sel_hi:[1,0,0]
	v_pk_fma_f32 v[30:31], v[30:31], v[172:173], v[172:173] op_sel_hi:[1,0,0]
	v_pk_fma_f32 v[20:21], v[20:21], v[172:173], v[172:173] op_sel_hi:[1,0,0]
	v_pk_fma_f32 v[22:23], v[22:23], v[172:173], v[172:173] op_sel_hi:[1,0,0]
	v_rcp_f32_e32 v28, v28
	v_rcp_f32_e32 v29, v29
	v_rcp_f32_e32 v30, v30
	v_rcp_f32_e32 v31, v31
	v_rcp_f32_e32 v20, v20
	v_rcp_f32_e32 v21, v21
	v_rcp_f32_e32 v22, v22
	v_rcp_f32_e32 v23, v23
	v_pk_mul_f32 v[24:25], v[24:25], v[28:29]
	v_pk_mul_f32 v[26:27], v[26:27], v[30:31]
	v_pk_mul_f32 v[16:17], v[16:17], v[20:21]
	v_pk_mul_f32 v[18:19], v[18:19], v[22:23]
	v_cvt_pk_bf16_f32 v208, v24, v25
	v_cvt_pk_bf16_f32 v209, v26, v27
	v_cvt_pk_bf16_f32 v210, v16, v17
	v_cvt_pk_bf16_f32 v211, v18, v19
	v_lshl_add_u64 v[176:177], s[68:69], 0, v[134:135]
	global_store_dwordx4 v[176:177], v[208:211], off sc1
	v_pk_mul_f32 v[12:13], v[12:13], v[174:175] op_sel:[0,1] op_sel_hi:[1,1]
	v_pk_mul_f32 v[14:15], v[14:15], v[174:175] op_sel:[0,1] op_sel_hi:[1,1]
	v_pk_mul_f32 v[4:5], v[4:5], v[174:175] op_sel:[0,1] op_sel_hi:[1,1]
	v_pk_mul_f32 v[6:7], v[6:7], v[174:175] op_sel:[0,1] op_sel_hi:[1,1]
	v_exp_f32_e32 v12, v12
	v_exp_f32_e32 v13, v13
	v_exp_f32_e32 v14, v14
	v_exp_f32_e32 v15, v15
	v_exp_f32_e32 v4, v4
	v_exp_f32_e32 v5, v5
	v_exp_f32_e32 v6, v6
	v_exp_f32_e32 v7, v7
	v_pk_fma_f32 v[12:13], v[12:13], v[174:175], v[174:175] op_sel_hi:[1,0,0]
	v_pk_fma_f32 v[14:15], v[14:15], v[174:175], v[174:175] op_sel_hi:[1,0,0]
	v_pk_fma_f32 v[4:5], v[4:5], v[174:175], v[174:175] op_sel_hi:[1,0,0]
	v_pk_fma_f32 v[6:7], v[6:7], v[174:175], v[174:175] op_sel_hi:[1,0,0]
	v_rcp_f32_e32 v12, v12
	v_rcp_f32_e32 v13, v13
	v_rcp_f32_e32 v14, v14
	v_rcp_f32_e32 v15, v15
	v_rcp_f32_e32 v4, v4
	v_rcp_f32_e32 v5, v5
	v_rcp_f32_e32 v6, v6
	v_rcp_f32_e32 v7, v7
	v_pk_mul_f32 v[8:9], v[8:9], v[12:13]
	v_pk_mul_f32 v[10:11], v[10:11], v[14:15]
	v_pk_mul_f32 v[0:1], v[0:1], v[4:5]
	v_pk_mul_f32 v[2:3], v[2:3], v[6:7]
	v_cvt_pk_bf16_f32 v212, v8, v9
	v_cvt_pk_bf16_f32 v213, v10, v11
	v_cvt_pk_bf16_f32 v214, v0, v1
	v_cvt_pk_bf16_f32 v215, v2, v3
	v_lshl_add_u64 v[176:177], s[68:69], 0, v[136:137]
	global_store_dwordx4 v[176:177], v[212:215], off sc1
	s_andn2_b64 vcc, exec, s[2:3]
	s_mov_b64 s[2:3], -1
	s_cbranch_vccnz .LBB0_137
	s_andn2_b64 vcc, exec, s[52:53]
	s_cbranch_vccnz .LBB0_136
	s_branch .LBB0_136

; #define PG8_BAR __builtin_amdgcn_s_barrier()
;     __device__ __forceinline__ char* hb_at(const Unit& u, int ai, int m, int bj, int wr, int wc, int fr, int fq) const {
;         return (char*)hb + ((size_t)((u.pm * 16 + u.pn * 4 + bj * 2 + (wc >> 1)) * 2 + ai) * HTB) + lds_byte(wr * 64 + m * 16 + fr, (wc & 1) * 32 + 8 * fq); }
;     __device__ __forceinline__ void operator()(f32x4 (&acc)[2][2][4][2], const Unit& u, int wr, int wc, int fr, int fq) const {
;         const int row0 = u.pm * BM + wr * 64 + fr, col0 = u.pn * BM + wc * 32 + 8 * fq;
;         u32x4 pre[2][4][2];
; #pragma unroll
;         for (int ai = 0; ai < 2; ++ai)
; #pragma unroll
;             for (int m = 0; m < 4; ++m)
; #pragma unroll
;                 for (int bj = 0; bj < 2; ++bj) pre[ai][m][bj] = *(const u32x4*)hb_at(u, ai, m, bj, wr, wc, fr, fq);
; template <class Epi, class Sched, bool ALIGN_EPI = false, bool SP2 = false>
; __device__ __forceinline__ void gemm_phase(PG8_LAS unsigned char* lds, const Gemm g, const Sched& S, const Epi& E) {
;     ...
;         if constexpr (ALIGN_EPI) { if (wr == 0) PG8_BAR; }
.LBB0_229:
	s_lshl_b32 s8, s72, 3
	s_lshl_b32 s9, s76, 5
	s_add_i32 s9, s9, s8
	s_or_b32 s8, s9, s81
	s_ashr_i32 s9, s8, 31
	s_or_b32 s68, s8, 4
	s_lshl_b64 s[72:73], s[8:9], 14
	s_ashr_i32 s69, s68, 31
	v_lshl_add_u64 v[112:113], v[198:199], 0, s[72:73]
	s_lshl_b64 s[74:75], s[68:69], 14
	global_load_dwordx4 v[220:223], v[112:113], off
	v_lshl_add_u64 v[112:113], v[198:199], 0, s[74:75]
	global_load_dwordx4 v[224:227], v[112:113], off
	s_or_b32 s68, s8, 1
	s_or_b32 s8, s8, 5
	s_ashr_i32 s69, s68, 31
	s_ashr_i32 s9, s8, 31
	s_lshl_b64 s[70:71], s[68:69], 14
	s_lshl_b64 s[68:69], s[8:9], 14
	v_lshl_add_u64 v[112:113], v[200:201], 0, s[72:73]
	v_lshl_add_u64 v[114:115], v[202:203], 0, s[72:73]
	v_lshl_add_u64 v[124:125], v[196:197], 0, s[72:73]
	v_lshl_add_u64 v[126:127], v[200:201], 0, s[74:75]
	v_lshl_add_u64 v[136:137], v[202:203], 0, s[74:75]
	v_lshl_add_u64 v[138:139], v[196:197], 0, s[74:75]
	v_lshl_add_u64 v[140:141], v[198:199], 0, s[70:71]
	v_lshl_add_u64 v[142:143], v[198:199], 0, s[68:69]
	v_lshl_add_u64 v[144:145], v[200:201], 0, s[70:71]
	v_lshl_add_u64 v[146:147], v[200:201], 0, s[68:69]
	v_lshl_add_u64 v[216:217], v[202:203], 0, s[70:71]
	v_lshl_add_u64 v[228:229], v[202:203], 0, s[68:69]
	v_lshl_add_u64 v[230:231], v[196:197], 0, s[70:71]
	v_lshl_add_u64 v[232:233], v[196:197], 0, s[68:69]
	global_load_dwordx4 v[180:183], v[112:113], off
	global_load_dwordx4 v[176:179], v[126:127], off
	global_load_dwordx4 v[172:175], v[114:115], off
	global_load_dwordx4 v[168:171], v[136:137], off
	global_load_dwordx4 v[164:167], v[124:125], off
	global_load_dwordx4 v[160:163], v[138:139], off
	global_load_dwordx4 v[156:159], v[140:141], off
	global_load_dwordx4 v[152:155], v[142:143], off
	global_load_dwordx4 v[148:151], v[144:145], off
	s_nop 0
	global_load_dwordx4 v[144:147], v[146:147], off
	s_nop 0
	global_load_dwordx4 v[140:143], v[216:217], off
	global_load_dwordx4 v[136:139], v[228:229], off
	global_load_dwordx4 v[124:127], v[230:231], off
	global_load_dwordx4 v[112:115], v[232:233], off
	s_add_u32 s72, s12, s72
	s_addc_u32 s73, s13, s73
	v_lshl_add_u64 v[216:217], s[72:73], 0, v[190:191]
	s_add_u32 s74, s12, s74
	v_lshl_add_u32 v208, s76, 8, v189
	s_addc_u32 s75, s13, s75
	s_cmp_lg_u64 s[4:5], 0
	s_cbranch_scc0 .Lnoal_1
	v_readlane_b32 s99, v246, 6
	s_nop 1
	s_cmp_lt_u32 s99, 4
	s_cbranch_scc0 .Lnoal_1
	s_barrier

; #define PG8_BAR __builtin_amdgcn_s_barrier()
; template <class Epi, class Sched, bool ALIGN_EPI = false, bool SP2 = false>
; __device__ __forceinline__ void gemm_phase(PG8_LAS unsigned char* lds, const Gemm g, const Sched& S, const Epi& E) {
;     ...
;         if (!has_next) break;
; #pragma unroll
;         for (int a = 0; a < 2; ++a)
; #pragma unroll
;             for (int b = 0; b < 2; ++b)
; #pragma unroll
;                 for (int m = 0; m < 4; ++m)
; #pragma unroll
;                     for (int n = 0; n < 2; ++n) acc[a][b][m][n] = (f32x4){0.f, 0.f, 0.f, 0.f};
;         cur = nxt; cA = nA; cB = nB; ++ui;
;         if constexpr (ALIGN_EPI) { if (wr == 1) PG8_BAR; }
.LBB0_245:
	s_or_b64 exec, exec, s[68:69]
	s_and_b64 vcc, exec, s[4:5]
	s_mov_b64 s[4:5], -1
	s_cbranch_vccnz .LBB0_214
	s_andn2_b64 vcc, exec, s[56:57]
	s_cbranch_vccnz .LBB0_213
	s_branch .LBB0_213

; #define PG8_BAR __builtin_amdgcn_s_barrier()
;     __device__ __forceinline__ void operator()(f32x4 (&acc)[2][2][4][2], const Unit& u, int wr, int wc, int fr, int fq) const {
;         const int row0 = u.pm * BM + wr * 64 + fr, col0 = u.pn * BM + wc * 32 + 8 * fq;
;         const bool sig = u.pn >= 7; const float sc = u.pn < 4 ? qscale : 1.f;
;         float sq[2][4];
; #pragma unroll
;         for (int ai = 0; ai < 2; ++ai)
; #pragma unroll
;             for (int m = 0; m < 4; ++m) sq[ai][m] = ssq[row0 + ai * HALF + m * 16];
; template <class Epi, class Sched, bool ALIGN_EPI = false, bool SP2 = false>
; __device__ __forceinline__ void gemm_phase(PG8_LAS unsigned char* lds, const Gemm g, const Sched& S, const Epi& E) {
;     ...
;         if constexpr (ALIGN_EPI) { if (wr == 0) PG8_BAR; }
.LBB0_318:
	v_lshl_add_u32 v140, s72, 8, v157
	v_ashrrev_i32_e32 v141, 31, v140
	v_lshl_add_u64 v[2:3], v[140:141], 2, s[10:11]
	v_or_b32_e32 v148, 16, v140
	global_load_dword v1, v[2:3], off
	v_ashrrev_i32_e32 v149, 31, v148
	v_or_b32_e32 v146, 32, v140
	v_or_b32_e32 v144, 48, v140
	v_lshl_add_u64 v[142:143], v[148:149], 2, s[10:11]
	v_ashrrev_i32_e32 v147, 31, v146
	v_ashrrev_i32_e32 v145, 31, v144
	v_lshl_add_u64 v[150:151], v[146:147], 2, s[10:11]
	v_lshl_add_u64 v[152:153], v[144:145], 2, s[10:11]
	global_load_dword v169, v[142:143], off
	global_load_dword v168, v[150:151], off
	global_load_dword v167, v[152:153], off
	global_load_dword v166, v[2:3], off offset:512
	global_load_dword v149, v[2:3], off offset:576
	global_load_dword v147, v[2:3], off offset:640
	global_load_dword v141, v[2:3], off offset:704
	s_cmp_gt_i32 s6, 6
	s_cselect_b64 s[74:75], -1, 0
	s_cmp_lt_i32 s6, 7
	s_cselect_b64 s[76:77], -1, 0
	s_cmp_lt_i32 s6, 4
	s_cselect_b64 vcc, -1, 0
	v_lshl_or_b32 v142, s6, 8, v158
	v_mad_i64_i32 v[2:3], s[8:9], v140, s81, 0
	v_cndmask_b32_e32 v145, 1.0, v165, vcc
	v_ashrrev_i32_e32 v143, 31, v142
	v_lshl_add_u64 v[2:3], s[28:29], 0, v[2:3]
	s_mov_b64 s[4:5], -1
	s_and_b64 vcc, exec, s[76:77]
	v_lshl_add_u64 v[150:151], v[142:143], 1, v[2:3]
	s_cmp_lg_u64 s[2:3], 0
	s_cbranch_scc1 .Lnoal_2
	v_readlane_b32 s99, v246, 6
	s_nop 1
	s_cmp_lt_u32 s99, 4
	s_cbranch_scc0 .Lnoal_2
	s_barrier

; #define PG8_BAR __builtin_amdgcn_s_barrier()
; template <class Epi, class Sched, bool ALIGN_EPI = false, bool SP2 = false>
; __device__ __forceinline__ void gemm_phase(PG8_LAS unsigned char* lds, const Gemm g, const Sched& S, const Epi& E) {
;     ...
;         if (!has_next) break;
; #pragma unroll
;         for (int a = 0; a < 2; ++a)
; #pragma unroll
;             for (int b = 0; b < 2; ++b)
; #pragma unroll
;                 for (int m = 0; m < 4; ++m)
; #pragma unroll
;                     for (int n = 0; n < 2; ++n) acc[a][b][m][n] = (f32x4){0.f, 0.f, 0.f, 0.f};
;         cur = nxt; cA = nA; cB = nB; ++ui;
;         if constexpr (ALIGN_EPI) { if (wr == 1) PG8_BAR; }
.LBB0_407:
	s_andn2_b64 vcc, exec, s[56:57]
	s_cbranch_vccnz .LBB0_310
	s_branch .LBB0_310

; __device__ __forceinline__ float bf_lo(unsigned w) { return __uint_as_float(w << 16); }
; __device__ __forceinline__ float bf_hi(unsigned w) { return __uint_as_float(w & 0xffff0000u); }
;     __device__ __forceinline__ void operator()(f32x4 (&acc)[2][2][4][2], const Unit& u, int wr, int wc, int fr, int fq) const {
;         const int row0 = u.pm * BM + wr * 64 + fr, col0 = u.pn * BM + wc * 32 + 8 * fq;
;         const float q = 1.0f / 255.0f;
;         u32x4 gw[2][4];
; #pragma unroll
;         for (int ai = 0; ai < 2; ++ai)
; #pragma unroll
;             for (int m = 0; m < 4; ++m) gw[ai][m] = *(const u32x4*)(G8 + ((size_t)(((u.pm * 8 + gsel + u.pn) * 8 + (wr * 4 + wc)) * 8 + (ai * 4 + m)) * 1024) + (fq * 16 + fr) * 16);
;         if (ACCUM) {
;             int chain = row0; float dep = acc[0][0][0][0][0];
; #pragma unroll
;             for (int ai = 0; ai < 2; ++ai) { u32x4 ow[4][2];
;                 asm volatile("" : "+v"(chain) : "v"(dep));
; #pragma unroll
;                 for (int m = 0; m < 4; ++m)
; #pragma unroll
;                     for (int bj = 0; bj < 2; ++bj) ow[m][bj] = *(const u32x4*)(mg_at(u, ai, m, bj, wr, wc, fr, fq) + (chain - row0));
; #pragma unroll
;                 for (int m = 0; m < 4; ++m)
; #pragma unroll
;                     for (int bj = 0; bj < 2; ++bj) { const u32x4 gq = gw[ai][m]; u32x2 g; g.x = bj ? gq.z : gq.x; g.y = bj ? gq.w : gq.y; const u32x4 o = ow[m][bj]; f32x4& a0 = acc[ai][bj][m][0]; f32x4& a1 = acc[ai][bj][m][1];
;                         a0[0] = a0[0] * (ub(g.x, 0) * q) + bf_lo(o.x); a0[1] = a0[1] * (ub(g.x, 1) * q) + bf_hi(o.x); a0[2] = a0[2] * (ub(g.x, 2) * q) + bf_lo(o.y); a0[3] = a0[3] * (ub(g.x, 3) * q) + bf_hi(o.y);
;                         a1[0] = a1[0] * (ub(g.y, 0) * q) + bf_lo(o.z); a1[1] = a1[1] * (ub(g.y, 1) * q) + bf_hi(o.z); a1[2] = a1[2] * (ub(g.y, 2) * q) + bf_lo(o.w); a1[3] = a1[3] * (ub(g.y, 3) * q) + bf_hi(o.w);
;                         asm volatile("" : "+v"(a0), "+v"(a1)); }
;                 dep = acc[ai][1][3][1][3]; }
;         } else {
; #pragma unroll
;             for (int ai = 0; ai < 2; ++ai)
; #pragma unroll
;                 for (int m = 0; m < 4; ++m)
; #pragma unroll
;                     for (int bj = 0; bj < 2; ++bj) { const u32x4 gq = gw[ai][m]; u32x2 g; g.x = bj ? gq.z : gq.x; g.y = bj ? gq.w : gq.y; f32x4& a0 = acc[ai][bj][m][0]; f32x4& a1 = acc[ai][bj][m][1];
.LBB0_649:
	s_lshl_b32 s1, s89, 6
	s_lshl_b32 s0, s88, 9
	s_add_i32 s1, s76, s1
	s_add_i32 s0, s1, s0
	s_ashr_i32 s1, s0, 31
	s_lshl_b64 s[8:9], s[0:1], 10
	v_lshl_add_u64 v[128:129], v[172:173], 0, s[8:9]
	global_load_dwordx4 v[156:159], v[128:129], off
	s_or_b32 s8, s0, 1
	s_ashr_i32 s9, s8, 31
	s_lshl_b64 s[8:9], s[8:9], 10
	v_lshl_add_u64 v[128:129], v[172:173], 0, s[8:9]
	global_load_dwordx4 v[152:155], v[128:129], off
	s_or_b32 s8, s0, 2
	s_ashr_i32 s9, s8, 31
	s_lshl_b64 s[8:9], s[8:9], 10
	v_lshl_add_u64 v[128:129], v[172:173], 0, s[8:9]
	global_load_dwordx4 v[148:151], v[128:129], off
	s_or_b32 s8, s0, 3
	s_ashr_i32 s9, s8, 31
	s_lshl_b64 s[8:9], s[8:9], 10
	v_lshl_add_u64 v[128:129], v[172:173], 0, s[8:9]
	global_load_dwordx4 v[144:147], v[128:129], off
	s_or_b32 s8, s0, 4
	s_ashr_i32 s9, s8, 31
	s_lshl_b64 s[8:9], s[8:9], 10
	v_lshl_add_u64 v[128:129], v[172:173], 0, s[8:9]
	global_load_dwordx4 v[140:143], v[128:129], off
	s_or_b32 s8, s0, 5
	s_ashr_i32 s9, s8, 31
	s_lshl_b64 s[8:9], s[8:9], 10
	v_lshl_add_u64 v[128:129], v[172:173], 0, s[8:9]
	global_load_dwordx4 v[136:139], v[128:129], off
	s_or_b32 s8, s0, 6
	s_or_b32 s0, s0, 7
	s_ashr_i32 s1, s0, 31
	s_ashr_i32 s9, s8, 31
	s_lshl_b64 s[0:1], s[0:1], 10
	s_lshl_b64 s[8:9], s[8:9], 10
	v_lshl_add_u64 v[132:133], v[172:173], 0, s[0:1]
	global_load_dwordx4 v[132:135], v[132:133], off
	v_lshl_add_u64 v[128:129], v[172:173], 0, s[8:9]
	global_load_dwordx4 v[128:131], v[128:129], off
	s_lshl_b32 s0, s89, 3
	s_lshl_b32 s1, s88, 5
	s_add_i32 s1, s1, s0
	s_or_b32 s0, s1, s73
	s_ashr_i32 s1, s0, 31
	s_lshl_b64 s[8:9], s[0:1], 14
	s_add_u32 s66, s6, s8
	s_addc_u32 s67, s7, s9
	s_or_b32 s8, s0, 4
	s_ashr_i32 s9, s8, 31
	s_lshl_b64 s[8:9], s[8:9], 14
	s_add_u32 s68, s6, s8
	s_addc_u32 s69, s7, s9
	s_or_b32 s8, s0, 1
	s_ashr_i32 s9, s8, 31
	s_lshl_b64 s[8:9], s[8:9], 14
	s_cmp_lg_u64 s[2:3], 0
	s_cbranch_scc0 .Lnoal_3
	v_readlane_b32 s99, v246, 6
	s_nop 1
	s_cmp_lt_u32 s99, 4
	s_cbranch_scc0 .Lnoal_3
	s_barrier
.Lnoal_3:
	s_waitcnt vmcnt(0)
	v_cvt_f32_ubyte3_e32 v203, v156
	v_cvt_f32_ubyte2_e32 v202, v156
	v_cvt_f32_ubyte1_e32 v205, v156
	v_cvt_f32_ubyte0_e32 v204, v156
	v_pk_mul_f32 v[204:205], v[204:205], s[58:59] op_sel_hi:[1,0]
	v_pk_mul_f32 v[202:203], v[202:203], s[58:59] op_sel_hi:[1,0]
	v_pk_mul_f32 v[124:125], v[124:125], v[204:205]
	v_pk_mul_f32 v[126:127], v[126:127], v[202:203]
	v_cvt_f32_ubyte3_e32 v203, v157
	v_cvt_f32_ubyte2_e32 v202, v157
	v_cvt_f32_ubyte1_e32 v205, v157
	v_cvt_f32_ubyte0_e32 v204, v157
	v_pk_mul_f32 v[156:157], v[204:205], s[58:59] op_sel_hi:[1,0]
	v_pk_mul_f32 v[202:203], v[202:203], s[58:59] op_sel_hi:[1,0]
	v_pk_mul_f32 v[120:121], v[120:121], v[156:157]
	v_pk_mul_f32 v[122:123], v[122:123], v[202:203]
	v_cvt_f32_ubyte3_e32 v157, v158
	v_cvt_f32_ubyte2_e32 v156, v158
	v_cvt_f32_ubyte1_e32 v203, v158
	v_cvt_f32_ubyte0_e32 v202, v158
	v_pk_mul_f32 v[202:203], v[202:203], s[58:59] op_sel_hi:[1,0]
	v_pk_mul_f32 v[156:157], v[156:157], s[58:59] op_sel_hi:[1,0]
	v_pk_mul_f32 v[116:117], v[116:117], v[202:203]
	v_pk_mul_f32 v[118:119], v[118:119], v[156:157]
	v_cvt_f32_ubyte3_e32 v157, v159
	v_cvt_f32_ubyte2_e32 v156, v159
	v_cvt_f32_ubyte1_e32 v203, v159
	v_cvt_f32_ubyte0_e32 v202, v159
	v_pk_mul_f32 v[158:159], v[202:203], s[58:59] op_sel_hi:[1,0]
	v_pk_mul_f32 v[156:157], v[156:157], s[58:59] op_sel_hi:[1,0]
	v_pk_mul_f32 v[112:113], v[112:113], v[158:159]
	v_pk_mul_f32 v[114:115], v[114:115], v[156:157]
	v_cvt_f32_ubyte3_e32 v157, v152
	v_cvt_f32_ubyte2_e32 v156, v152
	v_cvt_f32_ubyte1_e32 v159, v152
	v_cvt_f32_ubyte0_e32 v158, v152
	v_pk_mul_f32 v[158:159], v[158:159], s[58:59] op_sel_hi:[1,0]
	v_pk_mul_f32 v[156:157], v[156:157], s[58:59] op_sel_hi:[1,0]
	v_pk_mul_f32 v[108:109], v[108:109], v[158:159]
	v_pk_mul_f32 v[110:111], v[110:111], v[156:157]
	v_cvt_f32_ubyte3_e32 v157, v153
	v_cvt_f32_ubyte2_e32 v156, v153
	v_cvt_f32_ubyte1_e32 v159, v153
	v_cvt_f32_ubyte0_e32 v158, v153
	v_pk_mul_f32 v[152:153], v[158:159], s[58:59] op_sel_hi:[1,0]
	v_pk_mul_f32 v[156:157], v[156:157], s[58:59] op_sel_hi:[1,0]
	v_pk_mul_f32 v[104:105], v[104:105], v[152:153]
	v_pk_mul_f32 v[106:107], v[106:107], v[156:157]
	v_cvt_f32_ubyte3_e32 v153, v154
	v_cvt_f32_ubyte2_e32 v152, v154
	v_cvt_f32_ubyte1_e32 v157, v154
	v_cvt_f32_ubyte0_e32 v156, v154
	v_pk_mul_f32 v[156:157], v[156:157], s[58:59] op_sel_hi:[1,0]
	v_pk_mul_f32 v[152:153], v[152:153], s[58:59] op_sel_hi:[1,0]
	v_pk_mul_f32 v[100:101], v[100:101], v[156:157]
	v_pk_mul_f32 v[102:103], v[102:103], v[152:153]
	v_cvt_f32_ubyte3_e32 v153, v155
	v_cvt_f32_ubyte2_e32 v152, v155
	v_cvt_f32_ubyte1_e32 v157, v155
	v_cvt_f32_ubyte0_e32 v156, v155
	v_pk_mul_f32 v[154:155], v[156:157], s[58:59] op_sel_hi:[1,0]
	v_pk_mul_f32 v[152:153], v[152:153], s[58:59] op_sel_hi:[1,0]
	v_pk_mul_f32 v[92:93], v[92:93], v[154:155]
	v_pk_mul_f32 v[94:95], v[94:95], v[152:153]
	v_cvt_f32_ubyte3_e32 v153, v148
	v_cvt_f32_ubyte2_e32 v152, v148
	v_cvt_f32_ubyte1_e32 v155, v148
	v_cvt_f32_ubyte0_e32 v154, v148
	v_pk_mul_f32 v[154:155], v[154:155], s[58:59] op_sel_hi:[1,0]
	v_pk_mul_f32 v[152:153], v[152:153], s[58:59] op_sel_hi:[1,0]
	v_pk_mul_f32 v[96:97], v[96:97], v[154:155]
	v_pk_mul_f32 v[98:99], v[98:99], v[152:153]
	v_cvt_f32_ubyte3_e32 v153, v149
	v_cvt_f32_ubyte2_e32 v152, v149
	v_cvt_f32_ubyte1_e32 v155, v149
	v_cvt_f32_ubyte0_e32 v154, v149
	v_pk_mul_f32 v[148:149], v[154:155], s[58:59] op_sel_hi:[1,0]
	v_pk_mul_f32 v[152:153], v[152:153], s[58:59] op_sel_hi:[1,0]
	v_pk_mul_f32 v[88:89], v[88:89], v[148:149]
	v_pk_mul_f32 v[90:91], v[90:91], v[152:153]
	v_cvt_f32_ubyte3_e32 v149, v150
	v_cvt_f32_ubyte2_e32 v148, v150
;     __device__ static __forceinline__ float ub(unsigned w, int k) { return (float)((w >> (8 * k)) & 0xffu); }
;     __device__ __forceinline__ void operator()(f32x4 (&acc)[2][2][4][2], const Unit& u, int wr, int wc, int fr, int fq) const {
;     ...
;             for (int ai = 0; ai < 2; ++ai)
; #pragma unroll
;                 for (int m = 0; m < 4; ++m)
; #pragma unroll
;                     for (int bj = 0; bj < 2; ++bj) { const u32x4 gq = gw[ai][m]; u32x2 g; g.x = bj ? gq.z : gq.x; g.y = bj ? gq.w : gq.y; f32x4& a0 = acc[ai][bj][m][0]; f32x4& a1 = acc[ai][bj][m][1];
;                         a0[0] *= ub(g.x, 0) * q; a0[1] *= ub(g.x, 1) * q; a0[2] *= ub(g.x, 2) * q; a0[3] *= ub(g.x, 3) * q; a1[0] *= ub(g.y, 0) * q; a1[1] *= ub(g.y, 1) * q; a1[2] *= ub(g.y, 2) * q; a1[3] *= ub(g.y, 3) * q;
;                         asm volatile("" : "+v"(a0), "+v"(a1)); }
	v_cvt_f32_ubyte1_e32 v153, v150
	v_cvt_f32_ubyte0_e32 v152, v150
	v_pk_mul_f32 v[152:153], v[152:153], s[58:59] op_sel_hi:[1,0]
	v_pk_mul_f32 v[148:149], v[148:149], s[58:59] op_sel_hi:[1,0]
	v_pk_mul_f32 v[84:85], v[84:85], v[152:153]
	v_pk_mul_f32 v[86:87], v[86:87], v[148:149]
	v_cvt_f32_ubyte3_e32 v149, v151
	v_cvt_f32_ubyte2_e32 v148, v151
	v_cvt_f32_ubyte1_e32 v153, v151
	v_cvt_f32_ubyte0_e32 v152, v151
	v_pk_mul_f32 v[150:151], v[152:153], s[58:59] op_sel_hi:[1,0]
	v_pk_mul_f32 v[148:149], v[148:149], s[58:59] op_sel_hi:[1,0]
	v_pk_mul_f32 v[76:77], v[76:77], v[150:151]
	v_pk_mul_f32 v[78:79], v[78:79], v[148:149]
	v_cvt_f32_ubyte3_e32 v149, v144
	v_cvt_f32_ubyte2_e32 v148, v144
	v_cvt_f32_ubyte1_e32 v151, v144
	v_cvt_f32_ubyte0_e32 v150, v144
	v_pk_mul_f32 v[150:151], v[150:151], s[58:59] op_sel_hi:[1,0]
	v_pk_mul_f32 v[148:149], v[148:149], s[58:59] op_sel_hi:[1,0]
	v_pk_mul_f32 v[80:81], v[80:81], v[150:151]
	v_pk_mul_f32 v[82:83], v[82:83], v[148:149]
	v_cvt_f32_ubyte3_e32 v149, v145
	v_cvt_f32_ubyte2_e32 v148, v145
	v_cvt_f32_ubyte1_e32 v151, v145
	v_cvt_f32_ubyte0_e32 v150, v145
	v_pk_mul_f32 v[144:145], v[150:151], s[58:59] op_sel_hi:[1,0]
	v_pk_mul_f32 v[148:149], v[148:149], s[58:59] op_sel_hi:[1,0]
	v_pk_mul_f32 v[72:73], v[72:73], v[144:145]
	v_pk_mul_f32 v[74:75], v[74:75], v[148:149]
	v_cvt_f32_ubyte3_e32 v145, v146
	v_cvt_f32_ubyte2_e32 v144, v146
	v_cvt_f32_ubyte1_e32 v149, v146
	v_cvt_f32_ubyte0_e32 v148, v146
	v_pk_mul_f32 v[148:149], v[148:149], s[58:59] op_sel_hi:[1,0]
	v_pk_mul_f32 v[144:145], v[144:145], s[58:59] op_sel_hi:[1,0]
	v_pk_mul_f32 v[68:69], v[68:69], v[148:149]
	v_pk_mul_f32 v[70:71], v[70:71], v[144:145]
	v_cvt_f32_ubyte3_e32 v145, v147
	v_cvt_f32_ubyte2_e32 v144, v147
	v_cvt_f32_ubyte1_e32 v149, v147
	v_cvt_f32_ubyte0_e32 v148, v147
	v_pk_mul_f32 v[146:147], v[148:149], s[58:59] op_sel_hi:[1,0]
	v_pk_mul_f32 v[144:145], v[144:145], s[58:59] op_sel_hi:[1,0]
	v_pk_mul_f32 v[64:65], v[64:65], v[146:147]
	v_pk_mul_f32 v[66:67], v[66:67], v[144:145]
	v_cvt_f32_ubyte3_e32 v145, v140
	v_cvt_f32_ubyte2_e32 v144, v140
	v_cvt_f32_ubyte1_e32 v147, v140
	v_cvt_f32_ubyte0_e32 v146, v140
	v_pk_mul_f32 v[146:147], v[146:147], s[58:59] op_sel_hi:[1,0]
	v_pk_mul_f32 v[144:145], v[144:145], s[58:59] op_sel_hi:[1,0]
	v_pk_mul_f32 v[60:61], v[60:61], v[146:147]
	v_pk_mul_f32 v[62:63], v[62:63], v[144:145]
	v_cvt_f32_ubyte3_e32 v145, v141
	v_cvt_f32_ubyte2_e32 v144, v141
	v_cvt_f32_ubyte1_e32 v147, v141
	v_cvt_f32_ubyte0_e32 v146, v141
	v_pk_mul_f32 v[140:141], v[146:147], s[58:59] op_sel_hi:[1,0]
	v_pk_mul_f32 v[144:145], v[144:145], s[58:59] op_sel_hi:[1,0]
	v_pk_mul_f32 v[56:57], v[56:57], v[140:141]
	v_pk_mul_f32 v[58:59], v[58:59], v[144:145]
	v_cvt_f32_ubyte3_e32 v141, v142
	v_cvt_f32_ubyte2_e32 v140, v142
	v_cvt_f32_ubyte1_e32 v145, v142
	v_cvt_f32_ubyte0_e32 v144, v142
	v_pk_mul_f32 v[144:145], v[144:145], s[58:59] op_sel_hi:[1,0]
	v_pk_mul_f32 v[140:141], v[140:141], s[58:59] op_sel_hi:[1,0]
	v_pk_mul_f32 v[52:53], v[52:53], v[144:145]
	v_pk_mul_f32 v[54:55], v[54:55], v[140:141]
	v_cvt_f32_ubyte3_e32 v141, v143
	v_cvt_f32_ubyte2_e32 v140, v143
	v_cvt_f32_ubyte1_e32 v145, v143
	v_cvt_f32_ubyte0_e32 v144, v143
	v_pk_mul_f32 v[142:143], v[144:145], s[58:59] op_sel_hi:[1,0]
	v_pk_mul_f32 v[140:141], v[140:141], s[58:59] op_sel_hi:[1,0]
	v_pk_mul_f32 v[44:45], v[44:45], v[142:143]
	v_pk_mul_f32 v[46:47], v[46:47], v[140:141]
	v_cvt_f32_ubyte3_e32 v141, v136
	v_cvt_f32_ubyte2_e32 v140, v136
	v_cvt_f32_ubyte1_e32 v143, v136
	v_cvt_f32_ubyte0_e32 v142, v136
	v_pk_mul_f32 v[142:143], v[142:143], s[58:59] op_sel_hi:[1,0]
	v_pk_mul_f32 v[140:141], v[140:141], s[58:59] op_sel_hi:[1,0]
	v_pk_mul_f32 v[48:49], v[48:49], v[142:143]
	v_pk_mul_f32 v[50:51], v[50:51], v[140:141]
	v_cvt_f32_ubyte3_e32 v141, v137
	v_cvt_f32_ubyte2_e32 v140, v137
	v_cvt_f32_ubyte1_e32 v143, v137
	v_cvt_f32_ubyte0_e32 v142, v137
	v_pk_mul_f32 v[136:137], v[142:143], s[58:59] op_sel_hi:[1,0]
	v_pk_mul_f32 v[140:141], v[140:141], s[58:59] op_sel_hi:[1,0]
	v_pk_mul_f32 v[40:41], v[40:41], v[136:137]
	v_pk_mul_f32 v[42:43], v[42:43], v[140:141]
	v_cvt_f32_ubyte3_e32 v137, v138
	v_cvt_f32_ubyte2_e32 v136, v138
	v_cvt_f32_ubyte1_e32 v141, v138
	v_cvt_f32_ubyte0_e32 v140, v138
	v_pk_mul_f32 v[140:141], v[140:141], s[58:59] op_sel_hi:[1,0]
	v_pk_mul_f32 v[136:137], v[136:137], s[58:59] op_sel_hi:[1,0]
	v_pk_mul_f32 v[36:37], v[36:37], v[140:141]
	v_pk_mul_f32 v[38:39], v[38:39], v[136:137]
	v_cvt_f32_ubyte3_e32 v137, v139
	v_cvt_f32_ubyte2_e32 v136, v139
	v_cvt_f32_ubyte1_e32 v141, v139
	v_cvt_f32_ubyte0_e32 v140, v139
	v_pk_mul_f32 v[138:139], v[140:141], s[58:59] op_sel_hi:[1,0]
	v_pk_mul_f32 v[136:137], v[136:137], s[58:59] op_sel_hi:[1,0]
	v_pk_mul_f32 v[28:29], v[28:29], v[138:139]
	v_pk_mul_f32 v[30:31], v[30:31], v[136:137]
	v_cvt_f32_ubyte3_e32 v137, v128
	v_cvt_f32_ubyte2_e32 v136, v128
	v_cvt_f32_ubyte1_e32 v139, v128
	v_cvt_f32_ubyte0_e32 v138, v128
	v_pk_mul_f32 v[138:139], v[138:139], s[58:59] op_sel_hi:[1,0]
	v_pk_mul_f32 v[136:137], v[136:137], s[58:59] op_sel_hi:[1,0]
	v_pk_mul_f32 v[32:33], v[32:33], v[138:139]
	v_pk_mul_f32 v[34:35], v[34:35], v[136:137]
	v_cvt_f32_ubyte3_e32 v137, v129
	v_cvt_f32_ubyte2_e32 v136, v129
	v_cvt_f32_ubyte1_e32 v139, v129
	v_cvt_f32_ubyte0_e32 v138, v129
	v_pk_mul_f32 v[128:129], v[138:139], s[58:59] op_sel_hi:[1,0]
	v_pk_mul_f32 v[136:137], v[136:137], s[58:59] op_sel_hi:[1,0]
	v_pk_mul_f32 v[24:25], v[24:25], v[128:129]
	v_pk_mul_f32 v[26:27], v[26:27], v[136:137]
	v_cvt_f32_ubyte3_e32 v129, v130
	v_cvt_f32_ubyte2_e32 v128, v130
	v_cvt_f32_ubyte1_e32 v137, v130
	v_cvt_f32_ubyte0_e32 v136, v130
; __device__ __forceinline__ unsigned cvt_pk_bf16(float lo, float hi) { unsigned r; asm volatile("v_cvt_pk_bf16_f32 %0, %1, %2" : "=v"(r) : "v"(lo), "v"(hi)); return r; }
;     __device__ static __forceinline__ float ub(unsigned w, int k) { return (float)((w >> (8 * k)) & 0xffu); }
; #define PG8_BAR __builtin_amdgcn_s_barrier()
;     __device__ __forceinline__ void operator()(f32x4 (&acc)[2][2][4][2], const Unit& u, int wr, int wc, int fr, int fq) const {
;     ...
;             for (int ai = 0; ai < 2; ++ai)
; #pragma unroll
;                 for (int m = 0; m < 4; ++m)
; #pragma unroll
;                     for (int bj = 0; bj < 2; ++bj) { const u32x4 gq = gw[ai][m]; u32x2 g; g.x = bj ? gq.z : gq.x; g.y = bj ? gq.w : gq.y; f32x4& a0 = acc[ai][bj][m][0]; f32x4& a1 = acc[ai][bj][m][1];
;                         a0[0] *= ub(g.x, 0) * q; a0[1] *= ub(g.x, 1) * q; a0[2] *= ub(g.x, 2) * q; a0[3] *= ub(g.x, 3) * q; a1[0] *= ub(g.y, 0) * q; a1[1] *= ub(g.y, 1) * q; a1[2] *= ub(g.y, 2) * q; a1[3] *= ub(g.y, 3) * q;
;                         asm volatile("" : "+v"(a0), "+v"(a1)); }
;         }
; #pragma unroll
;         for (int ai = 0; ai < 2; ++ai)
; #pragma unroll
;             for (int m = 0; m < 4; ++m)
; #pragma unroll
;                 for (int bj = 0; bj < 2; ++bj) { const f32x4 a0 = acc[ai][bj][m][0], a1 = acc[ai][bj][m][1];
;                     u32x4 w; w.x = cvt_pk_bf16(a0[0], a0[1]); w.y = cvt_pk_bf16(a0[2], a0[3]); w.z = cvt_pk_bf16(a1[0], a1[1]); w.w = cvt_pk_bf16(a1[2], a1[3]);
;                     *(u32x4*)mg_at(u, ai, m, bj, wr, wc, fr, fq) = w; }
; template <class Epi, class Sched, bool ALIGN_EPI = false, bool SP2 = false>
; __device__ __forceinline__ void gemm_phase(PG8_LAS unsigned char* lds, const Gemm g, const Sched& S, const Epi& E) {
;     ...
;         if (!has_next) break;
; #pragma unroll
;         for (int a = 0; a < 2; ++a)
; #pragma unroll
;             for (int b = 0; b < 2; ++b)
; #pragma unroll
;                 for (int m = 0; m < 4; ++m)
; #pragma unroll
;                     for (int n = 0; n < 2; ++n) acc[a][b][m][n] = (f32x4){0.f, 0.f, 0.f, 0.f};
;         cur = nxt; cA = nA; cB = nB; ++ui;
;         if constexpr (ALIGN_EPI) { if (wr == 1) PG8_BAR; }
	v_pk_mul_f32 v[136:137], v[136:137], s[58:59] op_sel_hi:[1,0]
	v_pk_mul_f32 v[128:129], v[128:129], s[58:59] op_sel_hi:[1,0]
	v_pk_mul_f32 v[20:21], v[20:21], v[136:137]
	v_pk_mul_f32 v[22:23], v[22:23], v[128:129]
	v_cvt_f32_ubyte3_e32 v129, v131
	v_cvt_f32_ubyte2_e32 v128, v131
	v_cvt_f32_ubyte1_e32 v137, v131
	v_cvt_f32_ubyte0_e32 v136, v131
	v_pk_mul_f32 v[130:131], v[136:137], s[58:59] op_sel_hi:[1,0]
	v_pk_mul_f32 v[128:129], v[128:129], s[58:59] op_sel_hi:[1,0]
	v_pk_mul_f32 v[12:13], v[12:13], v[130:131]
	v_pk_mul_f32 v[14:15], v[14:15], v[128:129]
	v_cvt_f32_ubyte3_e32 v129, v132
	v_cvt_f32_ubyte2_e32 v128, v132
	v_cvt_f32_ubyte1_e32 v131, v132
	v_cvt_f32_ubyte0_e32 v130, v132
	v_pk_mul_f32 v[130:131], v[130:131], s[58:59] op_sel_hi:[1,0]
	v_pk_mul_f32 v[128:129], v[128:129], s[58:59] op_sel_hi:[1,0]
	v_pk_mul_f32 v[16:17], v[16:17], v[130:131]
	v_pk_mul_f32 v[18:19], v[18:19], v[128:129]
	v_cvt_f32_ubyte3_e32 v129, v133
	v_cvt_f32_ubyte2_e32 v128, v133
	v_cvt_f32_ubyte1_e32 v131, v133
	v_cvt_f32_ubyte0_e32 v130, v133
	v_pk_mul_f32 v[130:131], v[130:131], s[58:59] op_sel_hi:[1,0]
	v_pk_mul_f32 v[128:129], v[128:129], s[58:59] op_sel_hi:[1,0]
	v_pk_mul_f32 v[8:9], v[8:9], v[130:131]
	v_pk_mul_f32 v[10:11], v[10:11], v[128:129]
	v_cvt_f32_ubyte3_e32 v129, v134
	v_cvt_f32_ubyte2_e32 v128, v134
	v_cvt_f32_ubyte1_e32 v131, v134
	v_cvt_f32_ubyte0_e32 v130, v134
	v_pk_mul_f32 v[130:131], v[130:131], s[58:59] op_sel_hi:[1,0]
	v_pk_mul_f32 v[128:129], v[128:129], s[58:59] op_sel_hi:[1,0]
	v_pk_mul_f32 v[4:5], v[4:5], v[130:131]
	v_pk_mul_f32 v[6:7], v[6:7], v[128:129]
	v_cvt_f32_ubyte3_e32 v129, v135
	v_cvt_f32_ubyte2_e32 v128, v135
	v_cvt_f32_ubyte1_e32 v131, v135
	v_cvt_f32_ubyte0_e32 v130, v135
	v_pk_mul_f32 v[130:131], v[130:131], s[58:59] op_sel_hi:[1,0]
	v_pk_mul_f32 v[128:129], v[128:129], s[58:59] op_sel_hi:[1,0]
	v_pk_mul_f32 v[0:1], v[0:1], v[130:131]
	v_pk_mul_f32 v[2:3], v[2:3], v[128:129]
	s_nop 0
	v_cvt_pk_bf16_f32 v124, v124, v125
	v_cvt_pk_bf16_f32 v125, v126, v127
	v_cvt_pk_bf16_f32 v126, v120, v121
	v_lshl_add_u64 v[120:121], s[66:67], 0, v[164:165]
	v_cvt_pk_bf16_f32 v127, v122, v123
	global_store_dwordx4 v[120:121], v[124:127], off sc1
	v_cvt_pk_bf16_f32 v116, v116, v117
	v_cvt_pk_bf16_f32 v117, v118, v119
	v_cvt_pk_bf16_f32 v118, v112, v113
	v_lshl_add_u64 v[112:113], s[68:69], 0, v[164:165]
	v_cvt_pk_bf16_f32 v119, v114, v115
	global_store_dwordx4 v[112:113], v[116:119], off sc1
	v_cvt_pk_bf16_f32 v108, v108, v109
	v_cvt_pk_bf16_f32 v109, v110, v111
	v_cvt_pk_bf16_f32 v110, v104, v105
	v_lshl_add_u64 v[104:105], s[66:67], 0, v[166:167]
	v_cvt_pk_bf16_f32 v111, v106, v107
	global_store_dwordx4 v[104:105], v[108:111], off sc1
	v_cvt_pk_bf16_f32 v100, v100, v101
	v_cvt_pk_bf16_f32 v101, v102, v103
	v_cvt_pk_bf16_f32 v102, v92, v93
	v_lshl_add_u64 v[92:93], s[68:69], 0, v[166:167]
	v_cvt_pk_bf16_f32 v103, v94, v95
	global_store_dwordx4 v[92:93], v[100:103], off sc1
	v_cvt_pk_bf16_f32 v92, v96, v97
	v_cvt_pk_bf16_f32 v93, v98, v99
	v_cvt_pk_bf16_f32 v94, v88, v89
	v_lshl_add_u64 v[88:89], s[66:67], 0, v[168:169]
	v_cvt_pk_bf16_f32 v95, v90, v91
	global_store_dwordx4 v[88:89], v[92:95], off sc1
	v_cvt_pk_bf16_f32 v84, v84, v85
	v_cvt_pk_bf16_f32 v85, v86, v87
	v_cvt_pk_bf16_f32 v86, v76, v77
	v_lshl_add_u64 v[76:77], s[68:69], 0, v[168:169]
	v_cvt_pk_bf16_f32 v87, v78, v79
	global_store_dwordx4 v[76:77], v[84:87], off sc1
	v_cvt_pk_bf16_f32 v76, v80, v81
	v_cvt_pk_bf16_f32 v77, v82, v83
	v_cvt_pk_bf16_f32 v78, v72, v73
	v_lshl_add_u64 v[72:73], s[66:67], 0, v[170:171]
	s_add_u32 s66, s6, s8
	s_addc_u32 s67, s7, s9
	s_or_b32 s0, s0, 5
	s_ashr_i32 s1, s0, 31
	s_lshl_b64 s[0:1], s[0:1], 14
	v_cvt_pk_bf16_f32 v79, v74, v75
	global_store_dwordx4 v[72:73], v[76:79], off sc1
	v_cvt_pk_bf16_f32 v68, v68, v69
	v_cvt_pk_bf16_f32 v69, v70, v71
	v_cvt_pk_bf16_f32 v70, v64, v65
	v_lshl_add_u64 v[64:65], s[68:69], 0, v[170:171]
	s_add_u32 s0, s6, s0
	v_cvt_pk_bf16_f32 v71, v66, v67
	global_store_dwordx4 v[64:65], v[68:71], off sc1
	v_cvt_pk_bf16_f32 v60, v60, v61
	v_cvt_pk_bf16_f32 v61, v62, v63
	v_cvt_pk_bf16_f32 v62, v56, v57
	v_lshl_add_u64 v[56:57], s[66:67], 0, v[164:165]
	s_addc_u32 s1, s7, s1
	v_cvt_pk_bf16_f32 v63, v58, v59
	global_store_dwordx4 v[56:57], v[60:63], off sc1
	v_cvt_pk_bf16_f32 v52, v52, v53
	v_cvt_pk_bf16_f32 v53, v54, v55
	v_cvt_pk_bf16_f32 v54, v44, v45
	v_lshl_add_u64 v[44:45], s[0:1], 0, v[164:165]
	v_cvt_pk_bf16_f32 v55, v46, v47
	global_store_dwordx4 v[44:45], v[52:55], off sc1
	v_cvt_pk_bf16_f32 v44, v48, v49
	v_cvt_pk_bf16_f32 v45, v50, v51
	v_cvt_pk_bf16_f32 v46, v40, v41
	v_lshl_add_u64 v[40:41], s[66:67], 0, v[166:167]
	v_cvt_pk_bf16_f32 v47, v42, v43
	global_store_dwordx4 v[40:41], v[44:47], off sc1
	v_cvt_pk_bf16_f32 v36, v36, v37
	v_cvt_pk_bf16_f32 v37, v38, v39
	v_cvt_pk_bf16_f32 v38, v28, v29
	v_lshl_add_u64 v[28:29], s[0:1], 0, v[166:167]
	v_cvt_pk_bf16_f32 v39, v30, v31
	global_store_dwordx4 v[28:29], v[36:39], off sc1
	v_cvt_pk_bf16_f32 v28, v32, v33
	v_cvt_pk_bf16_f32 v29, v34, v35
	v_cvt_pk_bf16_f32 v30, v24, v25
	v_lshl_add_u64 v[24:25], s[66:67], 0, v[168:169]
	v_cvt_pk_bf16_f32 v31, v26, v27
	global_store_dwordx4 v[24:25], v[28:31], off sc1
	v_cvt_pk_bf16_f32 v20, v20, v21
	v_cvt_pk_bf16_f32 v21, v22, v23
	v_cvt_pk_bf16_f32 v22, v12, v13
	v_lshl_add_u64 v[12:13], s[0:1], 0, v[168:169]
	v_cvt_pk_bf16_f32 v23, v14, v15
	global_store_dwordx4 v[12:13], v[20:23], off sc1
	v_cvt_pk_bf16_f32 v12, v16, v17
	v_cvt_pk_bf16_f32 v13, v18, v19
	v_cvt_pk_bf16_f32 v14, v8, v9
	v_lshl_add_u64 v[8:9], s[66:67], 0, v[170:171]
	v_cvt_pk_bf16_f32 v15, v10, v11
	global_store_dwordx4 v[8:9], v[12:15], off sc1
	v_cvt_pk_bf16_f32 v4, v4, v5
	v_cvt_pk_bf16_f32 v5, v6, v7
	v_cvt_pk_bf16_f32 v6, v0, v1
	v_lshl_add_u64 v[0:1], s[0:1], 0, v[170:171]
	s_mov_b64 s[0:1], -1
	s_and_b64 vcc, exec, s[2:3]
	v_cvt_pk_bf16_f32 v7, v2, v3
	global_store_dwordx4 v[0:1], v[4:7], off sc1
	s_cbranch_vccnz .LBB0_636
	s_andn2_b64 vcc, exec, s[54:55]
	s_cbranch_vccnz .LBB0_635
	s_branch .LBB0_635

; __device__ __forceinline__ float bf_lo(unsigned w) { return __uint_as_float(w << 16); }
; __device__ __forceinline__ float bf_hi(unsigned w) { return __uint_as_float(w & 0xffff0000u); }
;     __device__ static __forceinline__ float ub(unsigned w, int k) { return (float)((w >> (8 * k)) & 0xffu); }
;     __device__ __forceinline__ void operator()(f32x4 (&acc)[2][2][4][2], const Unit& u, int wr, int wc, int fr, int fq) const {
;         const int row0 = u.pm * BM + wr * 64 + fr, col0 = u.pn * BM + wc * 32 + 8 * fq;
;         const float q = 1.0f / 255.0f;
;         u32x4 gw[2][4];
; #pragma unroll
;         for (int ai = 0; ai < 2; ++ai)
; #pragma unroll
;             for (int m = 0; m < 4; ++m) gw[ai][m] = *(const u32x4*)(G8 + ((size_t)(((u.pm * 8 + gsel + u.pn) * 8 + (wr * 4 + wc)) * 8 + (ai * 4 + m)) * 1024) + (fq * 16 + fr) * 16);
;         if (ACCUM) {
;             int chain = row0; float dep = acc[0][0][0][0][0];
; #pragma unroll
;             for (int ai = 0; ai < 2; ++ai) { u32x4 ow[4][2];
;                 asm volatile("" : "+v"(chain) : "v"(dep));
; #pragma unroll
;                 for (int m = 0; m < 4; ++m)
; #pragma unroll
;                     for (int bj = 0; bj < 2; ++bj) ow[m][bj] = *(const u32x4*)(mg_at(u, ai, m, bj, wr, wc, fr, fq) + (chain - row0));
; #pragma unroll
;                 for (int m = 0; m < 4; ++m)
; #pragma unroll
;                     for (int bj = 0; bj < 2; ++bj) { const u32x4 gq = gw[ai][m]; u32x2 g; g.x = bj ? gq.z : gq.x; g.y = bj ? gq.w : gq.y; const u32x4 o = ow[m][bj]; f32x4& a0 = acc[ai][bj][m][0]; f32x4& a1 = acc[ai][bj][m][1];
;                         a0[0] = a0[0] * (ub(g.x, 0) * q) + bf_lo(o.x); a0[1] = a0[1] * (ub(g.x, 1) * q) + bf_hi(o.x); a0[2] = a0[2] * (ub(g.x, 2) * q) + bf_lo(o.y); a0[3] = a0[3] * (ub(g.x, 3) * q) + bf_hi(o.y);
;                         a1[0] = a1[0] * (ub(g.y, 0) * q) + bf_lo(o.z); a1[1] = a1[1] * (ub(g.y, 1) * q) + bf_hi(o.z); a1[2] = a1[2] * (ub(g.y, 2) * q) + bf_lo(o.w); a1[3] = a1[3] * (ub(g.y, 3) * q) + bf_hi(o.w);
;                         asm volatile("" : "+v"(a0), "+v"(a1)); }
;                 dep = acc[ai][1][3][1][3]; }
; template <class Epi, class Sched, bool ALIGN_EPI = false, bool SP2 = false>
; __device__ __forceinline__ void gemm_phase(PG8_LAS unsigned char* lds, const Gemm g, const Sched& S, const Epi& E) {
;     ...
;         if constexpr (ALIGN_EPI) { if (wr == 0) PG8_BAR; }
.LBB0_673:
	s_lshl_b32 s9, s63, 6
	s_lshl_b32 s8, s62, 9
	s_add_i32 s9, s77, s9
	s_add_i32 s8, s9, s8
	s_ashr_i32 s9, s8, 31
	s_lshl_b64 s[64:65], s[8:9], 10
	v_lshl_add_u64 v[108:109], v[184:185], 0, s[64:65]
	s_or_b32 s64, s8, 1
	s_ashr_i32 s65, s64, 31
	s_lshl_b64 s[64:65], s[64:65], 10
	v_lshl_add_u64 v[110:111], v[184:185], 0, s[64:65]
	s_or_b32 s64, s8, 2
	s_ashr_i32 s65, s64, 31
	s_lshl_b64 s[64:65], s[64:65], 10
	global_load_dwordx4 v[204:207], v[108:109], off
	global_load_dwordx4 v[164:167], v[110:111], off
	v_lshl_add_u64 v[108:109], v[184:185], 0, s[64:65]
	s_or_b32 s64, s8, 3
	s_ashr_i32 s65, s64, 31
	s_lshl_b64 s[64:65], s[64:65], 10
	v_lshl_add_u64 v[110:111], v[184:185], 0, s[64:65]
	s_or_b32 s64, s8, 4
	s_ashr_i32 s65, s64, 31
	s_lshl_b64 s[64:65], s[64:65], 10
	global_load_dwordx4 v[152:155], v[108:109], off
	global_load_dwordx4 v[144:147], v[110:111], off
	v_lshl_add_u64 v[108:109], v[184:185], 0, s[64:65]
	s_or_b32 s64, s8, 5
	s_ashr_i32 s65, s64, 31
	s_lshl_b64 s[64:65], s[64:65], 10
	v_lshl_add_u64 v[110:111], v[184:185], 0, s[64:65]
	s_or_b32 s64, s8, 6
	s_or_b32 s8, s8, 7
	s_ashr_i32 s65, s64, 31
	s_ashr_i32 s9, s8, 31
	s_lshl_b64 s[64:65], s[64:65], 10
	s_lshl_b64 s[8:9], s[8:9], 10
	v_lshl_add_u32 v219, s62, 8, v198
	global_load_dwordx4 v[140:143], v[108:109], off
	global_load_dwordx4 v[136:139], v[110:111], off
	v_lshl_add_u64 v[108:109], v[184:185], 0, s[64:65]
	v_lshl_add_u64 v[110:111], v[184:185], 0, s[8:9]
	s_lshl_b32 s8, s63, 3
	s_lshl_b32 s9, s62, 5
	v_mov_b32_e32 v236, v219
	global_load_dwordx4 v[132:135], v[108:109], off
	s_nop 0
	global_load_dwordx4 v[108:111], v[110:111], off
	s_add_i32 s9, s9, s8
	s_or_b32 s66, s9, s74
	v_sub_u32_e32 v148, v236, v219
	v_ashrrev_i32_e32 v149, 31, v148
	v_lshl_add_u64 v[148:149], s[6:7], 0, v[148:149]
	s_ashr_i32 s67, s66, 31
	s_lshl_b64 s[64:65], s[66:67], 14
	v_lshl_add_u64 v[150:151], v[148:149], 0, v[176:177]
	v_lshl_add_u64 v[156:157], v[150:151], 0, s[64:65]
	global_load_dwordx4 v[208:211], v[156:157], off
	s_or_b32 s8, s66, 4
	s_ashr_i32 s9, s8, 31
	s_lshl_b64 s[62:63], s[8:9], 14
	v_lshl_add_u64 v[150:151], v[150:151], 0, s[62:63]
	global_load_dwordx4 v[212:215], v[150:151], off
	v_lshl_add_u64 v[150:151], v[148:149], 0, v[178:179]
	v_lshl_add_u64 v[156:157], v[150:151], 0, s[64:65]
	global_load_dwordx4 v[220:223], v[156:157], off
	v_lshl_add_u64 v[156:157], v[148:149], 0, v[180:181]
	v_lshl_add_u64 v[148:149], v[148:149], 0, v[182:183]
	v_lshl_add_u64 v[150:151], v[150:151], 0, s[62:63]
	v_lshl_add_u64 v[158:159], v[156:157], 0, s[64:65]
	v_lshl_add_u64 v[156:157], v[156:157], 0, s[62:63]
	v_lshl_add_u64 v[216:217], v[148:149], 0, s[64:65]
	v_lshl_add_u64 v[148:149], v[148:149], 0, s[62:63]
	global_load_dwordx4 v[224:227], v[150:151], off
	global_load_dwordx4 v[168:171], v[158:159], off
	global_load_dwordx4 v[160:163], v[156:157], off
	s_nop 0
	global_load_dwordx4 v[156:159], v[216:217], off
	s_nop 0
	global_load_dwordx4 v[148:151], v[148:149], off
	s_or_b32 s8, s66, 1
	s_ashr_i32 s9, s8, 31
	s_lshl_b64 s[68:69], s[8:9], 14
	s_or_b32 s8, s66, 5
	s_ashr_i32 s9, s8, 31
	s_lshl_b64 s[66:67], s[8:9], 14
	s_add_u32 s64, s6, s64
	s_addc_u32 s65, s7, s65
	s_add_u32 s62, s6, s62
	s_addc_u32 s63, s7, s63
	s_cmp_lg_u64 s[2:3], 0
	s_cbranch_scc1 .Lnoal_4
	v_readlane_b32 s99, v246, 6
	s_nop 1
	s_cmp_lt_u32 s99, 4
	s_cbranch_scc0 .Lnoal_4
	s_barrier
.Lnoal_4:
	s_waitcnt vmcnt(0)
	v_cvt_f32_ubyte3_e32 v229, v204
	v_cvt_f32_ubyte2_e32 v228, v204
	v_pk_mul_f32 v[228:229], v[228:229], s[10:11] op_sel_hi:[1,0]
	v_cvt_f32_ubyte1_e32 v217, v204
	v_cvt_f32_ubyte0_e32 v216, v204
	v_cvt_f32_ubyte1_e32 v231, v205
	v_cvt_f32_ubyte0_e32 v230, v205
	v_pk_mul_f32 v[216:217], v[216:217], s[10:11] op_sel_hi:[1,0]
	v_pk_mul_f32 v[230:231], v[230:231], s[10:11] op_sel_hi:[1,0]
	v_lshlrev_b32_e32 v232, 16, v208
	v_and_b32_e32 v233, 0xffff0000, v208
	v_lshlrev_b32_e32 v208, 16, v209
	v_and_b32_e32 v209, 0xffff0000, v209
	v_pk_fma_f32 v[130:131], v[130:131], v[228:229], v[208:209]
	v_cvt_f32_ubyte3_e32 v209, v205
	v_cvt_f32_ubyte2_e32 v208, v205
	v_pk_mul_f32 v[204:205], v[208:209], s[10:11] op_sel_hi:[1,0]
	v_lshlrev_b32_e32 v208, 16, v211
	v_and_b32_e32 v209, 0xffff0000, v211
	v_pk_fma_f32 v[126:127], v[126:127], v[204:205], v[208:209]
	v_cvt_f32_ubyte1_e32 v205, v206
	v_cvt_f32_ubyte0_e32 v204, v206
	v_pk_mul_f32 v[204:205], v[204:205], s[10:11] op_sel_hi:[1,0]
	v_lshlrev_b32_e32 v208, 16, v212
	v_and_b32_e32 v209, 0xffff0000, v212
	v_pk_fma_f32 v[120:121], v[120:121], v[204:205], v[208:209]
	v_cvt_f32_ubyte3_e32 v205, v206
	v_cvt_f32_ubyte2_e32 v204, v206
	v_pk_mul_f32 v[204:205], v[204:205], s[10:11] op_sel_hi:[1,0]
	v_lshlrev_b32_e32 v208, 16, v213
	v_and_b32_e32 v209, 0xffff0000, v213
	v_pk_fma_f32 v[122:123], v[122:123], v[204:205], v[208:209]
	v_cvt_f32_ubyte1_e32 v205, v207
	v_cvt_f32_ubyte0_e32 v204, v207
	v_pk_mul_f32 v[204:205], v[204:205], s[10:11] op_sel_hi:[1,0]
	v_lshlrev_b32_e32 v208, 16, v214
	v_and_b32_e32 v209, 0xffff0000, v214
	v_pk_fma_f32 v[116:117], v[116:117], v[204:205], v[208:209]
	v_cvt_f32_ubyte3_e32 v205, v207
	v_cvt_f32_ubyte2_e32 v204, v207
	v_pk_mul_f32 v[204:205], v[204:205], s[10:11] op_sel_hi:[1,0]
	v_lshlrev_b32_e32 v206, 16, v215
	v_and_b32_e32 v207, 0xffff0000, v215
	v_pk_fma_f32 v[118:119], v[118:119], v[204:205], v[206:207]
	v_cvt_f32_ubyte1_e32 v205, v164
	v_cvt_f32_ubyte0_e32 v204, v164
	v_pk_mul_f32 v[204:205], v[204:205], s[10:11] op_sel_hi:[1,0]
	v_lshlrev_b32_e32 v206, 16, v220
	v_and_b32_e32 v207, 0xffff0000, v220
	v_pk_fma_f32 v[112:113], v[112:113], v[204:205], v[206:207]
	v_cvt_f32_ubyte3_e32 v205, v164
	v_cvt_f32_ubyte2_e32 v204, v164
; __device__ __forceinline__ float bf_lo(unsigned w) { return __uint_as_float(w << 16); }
; __device__ __forceinline__ float bf_hi(unsigned w) { return __uint_as_float(w & 0xffff0000u); }
;     __device__ static __forceinline__ float ub(unsigned w, int k) { return (float)((w >> (8 * k)) & 0xffu); }
;     __device__ __forceinline__ void operator()(f32x4 (&acc)[2][2][4][2], const Unit& u, int wr, int wc, int fr, int fq) const {
;     ...
;                     for (int bj = 0; bj < 2; ++bj) { const u32x4 gq = gw[ai][m]; u32x2 g; g.x = bj ? gq.z : gq.x; g.y = bj ? gq.w : gq.y; const u32x4 o = ow[m][bj]; f32x4& a0 = acc[ai][bj][m][0]; f32x4& a1 = acc[ai][bj][m][1];
;                         a0[0] = a0[0] * (ub(g.x, 0) * q) + bf_lo(o.x); a0[1] = a0[1] * (ub(g.x, 1) * q) + bf_hi(o.x); a0[2] = a0[2] * (ub(g.x, 2) * q) + bf_lo(o.y); a0[3] = a0[3] * (ub(g.x, 3) * q) + bf_hi(o.y);
;                         a1[0] = a1[0] * (ub(g.y, 0) * q) + bf_lo(o.z); a1[1] = a1[1] * (ub(g.y, 1) * q) + bf_hi(o.z); a1[2] = a1[2] * (ub(g.y, 2) * q) + bf_lo(o.w); a1[3] = a1[3] * (ub(g.y, 3) * q) + bf_hi(o.w);
;                         asm volatile("" : "+v"(a0), "+v"(a1)); }
	v_pk_mul_f32 v[204:205], v[204:205], s[10:11] op_sel_hi:[1,0]
	v_lshlrev_b32_e32 v206, 16, v221
	v_and_b32_e32 v207, 0xffff0000, v221
	v_pk_fma_f32 v[114:115], v[114:115], v[204:205], v[206:207]
	v_cvt_f32_ubyte1_e32 v205, v165
	v_cvt_f32_ubyte0_e32 v204, v165
	v_pk_mul_f32 v[204:205], v[204:205], s[10:11] op_sel_hi:[1,0]
	v_lshlrev_b32_e32 v206, 16, v222
	v_and_b32_e32 v207, 0xffff0000, v222
	v_pk_fma_f32 v[104:105], v[104:105], v[204:205], v[206:207]
	v_cvt_f32_ubyte3_e32 v205, v165
	v_cvt_f32_ubyte2_e32 v204, v165
	v_pk_mul_f32 v[164:165], v[204:205], s[10:11] op_sel_hi:[1,0]
	v_lshlrev_b32_e32 v204, 16, v223
	v_and_b32_e32 v205, 0xffff0000, v223
	v_pk_fma_f32 v[106:107], v[106:107], v[164:165], v[204:205]
	v_cvt_f32_ubyte1_e32 v165, v166
	v_cvt_f32_ubyte0_e32 v164, v166
	v_pk_mul_f32 v[164:165], v[164:165], s[10:11] op_sel_hi:[1,0]
	v_lshlrev_b32_e32 v204, 16, v224
	v_and_b32_e32 v205, 0xffff0000, v224
	v_pk_fma_f32 v[100:101], v[100:101], v[164:165], v[204:205]
	v_cvt_f32_ubyte3_e32 v165, v166
	v_cvt_f32_ubyte2_e32 v164, v166
	v_pk_mul_f32 v[164:165], v[164:165], s[10:11] op_sel_hi:[1,0]
	v_lshlrev_b32_e32 v204, 16, v225
	v_and_b32_e32 v205, 0xffff0000, v225
	v_pk_fma_f32 v[102:103], v[102:103], v[164:165], v[204:205]
	v_cvt_f32_ubyte1_e32 v165, v167
	v_cvt_f32_ubyte0_e32 v164, v167
	v_pk_mul_f32 v[164:165], v[164:165], s[10:11] op_sel_hi:[1,0]
	v_lshlrev_b32_e32 v204, 16, v226
	v_and_b32_e32 v205, 0xffff0000, v226
	v_pk_fma_f32 v[96:97], v[96:97], v[164:165], v[204:205]
	v_cvt_f32_ubyte3_e32 v165, v167
	v_cvt_f32_ubyte2_e32 v164, v167
	v_pk_mul_f32 v[164:165], v[164:165], s[10:11] op_sel_hi:[1,0]
	v_lshlrev_b32_e32 v166, 16, v227
	v_and_b32_e32 v167, 0xffff0000, v227
	v_pk_fma_f32 v[98:99], v[98:99], v[164:165], v[166:167]
	v_cvt_f32_ubyte1_e32 v165, v152
	v_cvt_f32_ubyte0_e32 v164, v152
	v_pk_mul_f32 v[164:165], v[164:165], s[10:11] op_sel_hi:[1,0]
	v_lshlrev_b32_e32 v166, 16, v168
	v_and_b32_e32 v167, 0xffff0000, v168
	v_pk_fma_f32 v[92:93], v[92:93], v[164:165], v[166:167]
	v_cvt_f32_ubyte3_e32 v165, v152
	v_cvt_f32_ubyte2_e32 v164, v152
	v_pk_mul_f32 v[164:165], v[164:165], s[10:11] op_sel_hi:[1,0]
	v_lshlrev_b32_e32 v166, 16, v169
	v_and_b32_e32 v167, 0xffff0000, v169
	v_pk_fma_f32 v[94:95], v[94:95], v[164:165], v[166:167]
	v_cvt_f32_ubyte1_e32 v165, v153
	v_cvt_f32_ubyte0_e32 v164, v153
	v_pk_mul_f32 v[164:165], v[164:165], s[10:11] op_sel_hi:[1,0]
	v_lshlrev_b32_e32 v166, 16, v170
	v_and_b32_e32 v167, 0xffff0000, v170
	v_pk_fma_f32 v[88:89], v[88:89], v[164:165], v[166:167]
	v_cvt_f32_ubyte3_e32 v165, v153
	v_cvt_f32_ubyte2_e32 v164, v153
	v_pk_mul_f32 v[152:153], v[164:165], s[10:11] op_sel_hi:[1,0]
	v_lshlrev_b32_e32 v164, 16, v171
	v_and_b32_e32 v165, 0xffff0000, v171
	v_pk_fma_f32 v[90:91], v[90:91], v[152:153], v[164:165]
	v_cvt_f32_ubyte1_e32 v153, v154
	v_cvt_f32_ubyte0_e32 v152, v154
	v_pk_mul_f32 v[152:153], v[152:153], s[10:11] op_sel_hi:[1,0]
	v_lshlrev_b32_e32 v164, 16, v160
	v_and_b32_e32 v165, 0xffff0000, v160
	v_pk_fma_f32 v[84:85], v[84:85], v[152:153], v[164:165]
	v_cvt_f32_ubyte3_e32 v153, v154
	v_cvt_f32_ubyte2_e32 v152, v154
	v_pk_mul_f32 v[152:153], v[152:153], s[10:11] op_sel_hi:[1,0]
	v_lshlrev_b32_e32 v160, 16, v161
	v_and_b32_e32 v161, 0xffff0000, v161
	v_pk_fma_f32 v[86:87], v[86:87], v[152:153], v[160:161]
	v_cvt_f32_ubyte1_e32 v153, v155
	v_cvt_f32_ubyte0_e32 v152, v155
	v_pk_mul_f32 v[152:153], v[152:153], s[10:11] op_sel_hi:[1,0]
	v_lshlrev_b32_e32 v160, 16, v162
	v_and_b32_e32 v161, 0xffff0000, v162
	v_pk_fma_f32 v[80:81], v[80:81], v[152:153], v[160:161]
	v_cvt_f32_ubyte3_e32 v153, v155
	v_cvt_f32_ubyte2_e32 v152, v155
	v_pk_mul_f32 v[152:153], v[152:153], s[10:11] op_sel_hi:[1,0]
	v_lshlrev_b32_e32 v154, 16, v163
	v_and_b32_e32 v155, 0xffff0000, v163
	v_pk_fma_f32 v[82:83], v[82:83], v[152:153], v[154:155]
	v_cvt_f32_ubyte1_e32 v153, v144
	v_cvt_f32_ubyte0_e32 v152, v144
	v_pk_mul_f32 v[152:153], v[152:153], s[10:11] op_sel_hi:[1,0]
	v_lshlrev_b32_e32 v154, 16, v156
	v_and_b32_e32 v155, 0xffff0000, v156
	v_pk_fma_f32 v[76:77], v[76:77], v[152:153], v[154:155]
	v_cvt_f32_ubyte3_e32 v153, v144
	v_cvt_f32_ubyte2_e32 v152, v144
	v_pk_mul_f32 v[152:153], v[152:153], s[10:11] op_sel_hi:[1,0]
	v_lshlrev_b32_e32 v154, 16, v157
	v_and_b32_e32 v155, 0xffff0000, v157
	v_pk_fma_f32 v[78:79], v[78:79], v[152:153], v[154:155]
	v_cvt_f32_ubyte1_e32 v153, v145
	v_cvt_f32_ubyte0_e32 v152, v145
	v_pk_mul_f32 v[152:153], v[152:153], s[10:11] op_sel_hi:[1,0]
	v_lshlrev_b32_e32 v154, 16, v158
	v_and_b32_e32 v155, 0xffff0000, v158
	v_pk_fma_f32 v[72:73], v[72:73], v[152:153], v[154:155]
	v_cvt_f32_ubyte3_e32 v153, v145
	v_cvt_f32_ubyte2_e32 v152, v145
	v_pk_mul_f32 v[144:145], v[152:153], s[10:11] op_sel_hi:[1,0]
	v_lshlrev_b32_e32 v152, 16, v159
	v_and_b32_e32 v153, 0xffff0000, v159
	v_pk_fma_f32 v[74:75], v[74:75], v[144:145], v[152:153]
	v_cvt_f32_ubyte1_e32 v145, v146
	v_cvt_f32_ubyte0_e32 v144, v146
	v_pk_mul_f32 v[144:145], v[144:145], s[10:11] op_sel_hi:[1,0]
	v_lshlrev_b32_e32 v152, 16, v148
	v_and_b32_e32 v153, 0xffff0000, v148
	v_pk_fma_f32 v[68:69], v[68:69], v[144:145], v[152:153]
	v_cvt_f32_ubyte3_e32 v145, v146
	v_cvt_f32_ubyte2_e32 v144, v146
	v_pk_mul_f32 v[144:145], v[144:145], s[10:11] op_sel_hi:[1,0]
	v_lshlrev_b32_e32 v148, 16, v149
	v_and_b32_e32 v149, 0xffff0000, v149
	v_pk_fma_f32 v[70:71], v[70:71], v[144:145], v[148:149]
	v_cvt_f32_ubyte1_e32 v145, v147
	v_cvt_f32_ubyte0_e32 v144, v147
	v_pk_mul_f32 v[144:145], v[144:145], s[10:11] op_sel_hi:[1,0]
	v_lshlrev_b32_e32 v148, 16, v150
	v_and_b32_e32 v149, 0xffff0000, v150
	v_pk_fma_f32 v[64:65], v[64:65], v[144:145], v[148:149]
; __device__ __forceinline__ float bf_lo(unsigned w) { return __uint_as_float(w << 16); }
; __device__ __forceinline__ float bf_hi(unsigned w) { return __uint_as_float(w & 0xffff0000u); }
;     __device__ static __forceinline__ float ub(unsigned w, int k) { return (float)((w >> (8 * k)) & 0xffu); }
;     __device__ __forceinline__ void operator()(f32x4 (&acc)[2][2][4][2], const Unit& u, int wr, int wc, int fr, int fq) const {
;     ...
;             for (int ai = 0; ai < 2; ++ai) { u32x4 ow[4][2];
;                 asm volatile("" : "+v"(chain) : "v"(dep));
; #pragma unroll
;                 for (int m = 0; m < 4; ++m)
; #pragma unroll
;                     for (int bj = 0; bj < 2; ++bj) ow[m][bj] = *(const u32x4*)(mg_at(u, ai, m, bj, wr, wc, fr, fq) + (chain - row0));
; #pragma unroll
;                 for (int m = 0; m < 4; ++m)
; #pragma unroll
;                     for (int bj = 0; bj < 2; ++bj) { const u32x4 gq = gw[ai][m]; u32x2 g; g.x = bj ? gq.z : gq.x; g.y = bj ? gq.w : gq.y; const u32x4 o = ow[m][bj]; f32x4& a0 = acc[ai][bj][m][0]; f32x4& a1 = acc[ai][bj][m][1];
;                         a0[0] = a0[0] * (ub(g.x, 0) * q) + bf_lo(o.x); a0[1] = a0[1] * (ub(g.x, 1) * q) + bf_hi(o.x); a0[2] = a0[2] * (ub(g.x, 2) * q) + bf_lo(o.y); a0[3] = a0[3] * (ub(g.x, 3) * q) + bf_hi(o.y);
;                         a1[0] = a1[0] * (ub(g.y, 0) * q) + bf_lo(o.z); a1[1] = a1[1] * (ub(g.y, 1) * q) + bf_hi(o.z); a1[2] = a1[2] * (ub(g.y, 2) * q) + bf_lo(o.w); a1[3] = a1[3] * (ub(g.y, 3) * q) + bf_hi(o.w);
;                         asm volatile("" : "+v"(a0), "+v"(a1)); }
	v_cvt_f32_ubyte3_e32 v145, v147
	v_cvt_f32_ubyte2_e32 v144, v147
	v_lshlrev_b32_e32 v234, 16, v210
	v_and_b32_e32 v235, 0xffff0000, v210
	v_pk_mul_f32 v[144:145], v[144:145], s[10:11] op_sel_hi:[1,0]
	v_lshlrev_b32_e32 v146, 16, v151
	v_and_b32_e32 v147, 0xffff0000, v151
	v_pk_fma_f32 v[128:129], v[128:129], v[216:217], v[232:233]
	v_pk_fma_f32 v[124:125], v[124:125], v[230:231], v[234:235]
	v_pk_fma_f32 v[66:67], v[66:67], v[144:145], v[146:147]
	s_nop 0
	v_cvt_f32_ubyte1_e32 v209, v140
	v_cvt_f32_ubyte0_e32 v208, v140
	v_sub_u32_e32 v144, v236, v219
	v_ashrrev_i32_e32 v145, 31, v144
	v_lshl_add_u64 v[144:145], s[6:7], 0, v[144:145]
	v_lshl_add_u64 v[146:147], v[144:145], 0, v[176:177]
	v_lshl_add_u64 v[148:149], v[146:147], 0, s[68:69]
	global_load_dwordx4 v[160:163], v[148:149], off
	v_lshl_add_u64 v[146:147], v[146:147], 0, s[66:67]
	global_load_dwordx4 v[164:167], v[146:147], off
	v_lshl_add_u64 v[146:147], v[144:145], 0, v[178:179]
	v_lshl_add_u64 v[148:149], v[146:147], 0, s[68:69]
	global_load_dwordx4 v[168:171], v[148:149], off
	v_lshl_add_u64 v[146:147], v[146:147], 0, s[66:67]
	global_load_dwordx4 v[204:207], v[146:147], off
	v_lshl_add_u64 v[146:147], v[144:145], 0, v[180:181]
	v_lshl_add_u64 v[148:149], v[146:147], 0, s[68:69]
	v_lshl_add_u64 v[146:147], v[146:147], 0, s[66:67]
	global_load_dwordx4 v[156:159], v[148:149], off
	global_load_dwordx4 v[152:155], v[146:147], off
	v_lshl_add_u64 v[144:145], v[144:145], 0, v[182:183]
	v_lshl_add_u64 v[146:147], v[144:145], 0, s[68:69]
	v_lshl_add_u64 v[144:145], v[144:145], 0, s[66:67]
	global_load_dwordx4 v[148:151], v[146:147], off
	s_nop 0
	global_load_dwordx4 v[144:147], v[144:145], off
	v_pk_mul_f32 v[208:209], v[208:209], s[10:11] op_sel_hi:[1,0]
	s_waitcnt vmcnt(7)
	v_lshlrev_b32_e32 v210, 16, v160
	v_and_b32_e32 v211, 0xffff0000, v160
	v_pk_fma_f32 v[60:61], v[60:61], v[208:209], v[210:211]
	v_cvt_f32_ubyte3_e32 v209, v140
	v_cvt_f32_ubyte2_e32 v208, v140
	v_pk_mul_f32 v[208:209], v[208:209], s[10:11] op_sel_hi:[1,0]
	v_lshlrev_b32_e32 v160, 16, v161
	v_and_b32_e32 v161, 0xffff0000, v161
	v_pk_fma_f32 v[62:63], v[62:63], v[208:209], v[160:161]
	v_cvt_f32_ubyte1_e32 v161, v141
	v_cvt_f32_ubyte0_e32 v160, v141
	v_pk_mul_f32 v[160:161], v[160:161], s[10:11] op_sel_hi:[1,0]
	v_lshlrev_b32_e32 v208, 16, v162
	v_and_b32_e32 v209, 0xffff0000, v162
	v_pk_fma_f32 v[56:57], v[56:57], v[160:161], v[208:209]
	v_cvt_f32_ubyte3_e32 v161, v141
	v_cvt_f32_ubyte2_e32 v160, v141
	v_pk_mul_f32 v[140:141], v[160:161], s[10:11] op_sel_hi:[1,0]
	v_lshlrev_b32_e32 v160, 16, v163
	v_and_b32_e32 v161, 0xffff0000, v163
	v_pk_fma_f32 v[58:59], v[58:59], v[140:141], v[160:161]
	v_cvt_f32_ubyte1_e32 v141, v142
	v_cvt_f32_ubyte0_e32 v140, v142
	v_pk_mul_f32 v[140:141], v[140:141], s[10:11] op_sel_hi:[1,0]
	s_waitcnt vmcnt(6)
	v_lshlrev_b32_e32 v160, 16, v164
	v_and_b32_e32 v161, 0xffff0000, v164
	v_pk_fma_f32 v[52:53], v[52:53], v[140:141], v[160:161]
	v_cvt_f32_ubyte3_e32 v141, v142
	v_cvt_f32_ubyte2_e32 v140, v142
	v_pk_mul_f32 v[140:141], v[140:141], s[10:11] op_sel_hi:[1,0]
	v_lshlrev_b32_e32 v160, 16, v165
	v_and_b32_e32 v161, 0xffff0000, v165
	v_pk_fma_f32 v[54:55], v[54:55], v[140:141], v[160:161]
	v_cvt_f32_ubyte1_e32 v141, v143
	v_cvt_f32_ubyte0_e32 v140, v143
	v_pk_mul_f32 v[140:141], v[140:141], s[10:11] op_sel_hi:[1,0]
	v_lshlrev_b32_e32 v160, 16, v166
	v_and_b32_e32 v161, 0xffff0000, v166
	v_pk_fma_f32 v[48:49], v[48:49], v[140:141], v[160:161]
	v_cvt_f32_ubyte3_e32 v141, v143
	v_cvt_f32_ubyte2_e32 v140, v143
	v_pk_mul_f32 v[140:141], v[140:141], s[10:11] op_sel_hi:[1,0]
	v_lshlrev_b32_e32 v142, 16, v167
	v_and_b32_e32 v143, 0xffff0000, v167
	v_pk_fma_f32 v[50:51], v[50:51], v[140:141], v[142:143]
	v_cvt_f32_ubyte1_e32 v141, v136
	v_cvt_f32_ubyte0_e32 v140, v136
	v_pk_mul_f32 v[140:141], v[140:141], s[10:11] op_sel_hi:[1,0]
	s_waitcnt vmcnt(5)
	v_lshlrev_b32_e32 v142, 16, v168
	v_and_b32_e32 v143, 0xffff0000, v168
	v_pk_fma_f32 v[44:45], v[44:45], v[140:141], v[142:143]
	v_cvt_f32_ubyte3_e32 v141, v136
	v_cvt_f32_ubyte2_e32 v140, v136
	v_pk_mul_f32 v[140:141], v[140:141], s[10:11] op_sel_hi:[1,0]
	v_lshlrev_b32_e32 v142, 16, v169
	v_and_b32_e32 v143, 0xffff0000, v169
	v_pk_fma_f32 v[46:47], v[46:47], v[140:141], v[142:143]
	v_cvt_f32_ubyte1_e32 v141, v137
	v_cvt_f32_ubyte0_e32 v140, v137
	v_pk_mul_f32 v[140:141], v[140:141], s[10:11] op_sel_hi:[1,0]
	v_lshlrev_b32_e32 v142, 16, v170
	v_and_b32_e32 v143, 0xffff0000, v170
	v_pk_fma_f32 v[40:41], v[40:41], v[140:141], v[142:143]
	v_cvt_f32_ubyte3_e32 v141, v137
	v_cvt_f32_ubyte2_e32 v140, v137
	v_pk_mul_f32 v[136:137], v[140:141], s[10:11] op_sel_hi:[1,0]
	v_lshlrev_b32_e32 v140, 16, v171
	v_and_b32_e32 v141, 0xffff0000, v171
	v_pk_fma_f32 v[42:43], v[42:43], v[136:137], v[140:141]
	v_cvt_f32_ubyte1_e32 v137, v138
	v_cvt_f32_ubyte0_e32 v136, v138
	v_pk_mul_f32 v[136:137], v[136:137], s[10:11] op_sel_hi:[1,0]
	s_waitcnt vmcnt(4)
	v_lshlrev_b32_e32 v140, 16, v204
	v_and_b32_e32 v141, 0xffff0000, v204
	v_pk_fma_f32 v[36:37], v[36:37], v[136:137], v[140:141]
	v_cvt_f32_ubyte3_e32 v137, v138
	v_cvt_f32_ubyte2_e32 v136, v138
	v_pk_mul_f32 v[136:137], v[136:137], s[10:11] op_sel_hi:[1,0]
	v_lshlrev_b32_e32 v140, 16, v205
	v_and_b32_e32 v141, 0xffff0000, v205
	v_pk_fma_f32 v[38:39], v[38:39], v[136:137], v[140:141]
	v_cvt_f32_ubyte1_e32 v137, v139
	v_cvt_f32_ubyte0_e32 v136, v139
	v_pk_mul_f32 v[136:137], v[136:137], s[10:11] op_sel_hi:[1,0]
	v_lshlrev_b32_e32 v140, 16, v206
	v_and_b32_e32 v141, 0xffff0000, v206
	v_pk_fma_f32 v[32:33], v[32:33], v[136:137], v[140:141]
	v_cvt_f32_ubyte3_e32 v137, v139
	v_cvt_f32_ubyte2_e32 v136, v139
	v_pk_mul_f32 v[136:137], v[136:137], s[10:11] op_sel_hi:[1,0]
	v_lshlrev_b32_e32 v138, 16, v207
	v_and_b32_e32 v139, 0xffff0000, v207
	v_pk_fma_f32 v[34:35], v[34:35], v[136:137], v[138:139]
	v_cvt_f32_ubyte1_e32 v137, v132
	v_cvt_f32_ubyte0_e32 v136, v132
	v_pk_mul_f32 v[136:137], v[136:137], s[10:11] op_sel_hi:[1,0]
	s_waitcnt vmcnt(3)
; __device__ __forceinline__ float bf_lo(unsigned w) { return __uint_as_float(w << 16); }
; __device__ __forceinline__ float bf_hi(unsigned w) { return __uint_as_float(w & 0xffff0000u); }
;     __device__ static __forceinline__ float ub(unsigned w, int k) { return (float)((w >> (8 * k)) & 0xffu); }
;     __device__ __forceinline__ void operator()(f32x4 (&acc)[2][2][4][2], const Unit& u, int wr, int wc, int fr, int fq) const {
;     ...
;                     for (int bj = 0; bj < 2; ++bj) { const u32x4 gq = gw[ai][m]; u32x2 g; g.x = bj ? gq.z : gq.x; g.y = bj ? gq.w : gq.y; const u32x4 o = ow[m][bj]; f32x4& a0 = acc[ai][bj][m][0]; f32x4& a1 = acc[ai][bj][m][1];
;                         a0[0] = a0[0] * (ub(g.x, 0) * q) + bf_lo(o.x); a0[1] = a0[1] * (ub(g.x, 1) * q) + bf_hi(o.x); a0[2] = a0[2] * (ub(g.x, 2) * q) + bf_lo(o.y); a0[3] = a0[3] * (ub(g.x, 3) * q) + bf_hi(o.y);
;                         a1[0] = a1[0] * (ub(g.y, 0) * q) + bf_lo(o.z); a1[1] = a1[1] * (ub(g.y, 1) * q) + bf_hi(o.z); a1[2] = a1[2] * (ub(g.y, 2) * q) + bf_lo(o.w); a1[3] = a1[3] * (ub(g.y, 3) * q) + bf_hi(o.w);
;                         asm volatile("" : "+v"(a0), "+v"(a1)); }
	v_lshlrev_b32_e32 v138, 16, v156
	v_and_b32_e32 v139, 0xffff0000, v156
	v_pk_fma_f32 v[28:29], v[28:29], v[136:137], v[138:139]
	v_cvt_f32_ubyte3_e32 v137, v132
	v_cvt_f32_ubyte2_e32 v136, v132
	v_pk_mul_f32 v[136:137], v[136:137], s[10:11] op_sel_hi:[1,0]
	v_lshlrev_b32_e32 v138, 16, v157
	v_and_b32_e32 v139, 0xffff0000, v157
	v_pk_fma_f32 v[30:31], v[30:31], v[136:137], v[138:139]
	v_cvt_f32_ubyte1_e32 v137, v133
	v_cvt_f32_ubyte0_e32 v136, v133
	v_pk_mul_f32 v[136:137], v[136:137], s[10:11] op_sel_hi:[1,0]
	v_lshlrev_b32_e32 v138, 16, v158
	v_and_b32_e32 v139, 0xffff0000, v158
	v_pk_fma_f32 v[24:25], v[24:25], v[136:137], v[138:139]
	v_cvt_f32_ubyte3_e32 v137, v133
	v_cvt_f32_ubyte2_e32 v136, v133
	v_pk_mul_f32 v[132:133], v[136:137], s[10:11] op_sel_hi:[1,0]
	v_lshlrev_b32_e32 v136, 16, v159
	v_and_b32_e32 v137, 0xffff0000, v159
	v_pk_fma_f32 v[26:27], v[26:27], v[132:133], v[136:137]
	v_cvt_f32_ubyte1_e32 v133, v134
	v_cvt_f32_ubyte0_e32 v132, v134
	v_pk_mul_f32 v[132:133], v[132:133], s[10:11] op_sel_hi:[1,0]
	s_waitcnt vmcnt(2)
	v_lshlrev_b32_e32 v136, 16, v152
	v_and_b32_e32 v137, 0xffff0000, v152
	v_pk_fma_f32 v[20:21], v[20:21], v[132:133], v[136:137]
	v_cvt_f32_ubyte3_e32 v133, v134
	v_cvt_f32_ubyte2_e32 v132, v134
	v_pk_mul_f32 v[132:133], v[132:133], s[10:11] op_sel_hi:[1,0]
	v_lshlrev_b32_e32 v136, 16, v153
	v_and_b32_e32 v137, 0xffff0000, v153
	v_pk_fma_f32 v[22:23], v[22:23], v[132:133], v[136:137]
	v_cvt_f32_ubyte1_e32 v133, v135
	v_cvt_f32_ubyte0_e32 v132, v135
	v_pk_mul_f32 v[132:133], v[132:133], s[10:11] op_sel_hi:[1,0]
	v_lshlrev_b32_e32 v136, 16, v154
	v_and_b32_e32 v137, 0xffff0000, v154
	v_pk_fma_f32 v[16:17], v[16:17], v[132:133], v[136:137]
	v_cvt_f32_ubyte3_e32 v133, v135
	v_cvt_f32_ubyte2_e32 v132, v135
	v_pk_mul_f32 v[132:133], v[132:133], s[10:11] op_sel_hi:[1,0]
	v_lshlrev_b32_e32 v134, 16, v155
	v_and_b32_e32 v135, 0xffff0000, v155
	v_pk_fma_f32 v[18:19], v[18:19], v[132:133], v[134:135]
	v_cvt_f32_ubyte1_e32 v133, v108
	v_cvt_f32_ubyte0_e32 v132, v108
	v_pk_mul_f32 v[132:133], v[132:133], s[10:11] op_sel_hi:[1,0]
	s_waitcnt vmcnt(1)
	v_lshlrev_b32_e32 v134, 16, v148
	v_and_b32_e32 v135, 0xffff0000, v148
	v_pk_fma_f32 v[12:13], v[12:13], v[132:133], v[134:135]
	v_cvt_f32_ubyte3_e32 v133, v108
	v_cvt_f32_ubyte2_e32 v132, v108
	v_pk_mul_f32 v[132:133], v[132:133], s[10:11] op_sel_hi:[1,0]
	v_lshlrev_b32_e32 v134, 16, v149
	v_and_b32_e32 v135, 0xffff0000, v149
	v_pk_fma_f32 v[14:15], v[14:15], v[132:133], v[134:135]
	v_cvt_f32_ubyte1_e32 v133, v109
	v_cvt_f32_ubyte0_e32 v132, v109
	v_pk_mul_f32 v[132:133], v[132:133], s[10:11] op_sel_hi:[1,0]
	v_lshlrev_b32_e32 v134, 16, v150
	v_and_b32_e32 v135, 0xffff0000, v150
	v_pk_fma_f32 v[8:9], v[8:9], v[132:133], v[134:135]
	v_cvt_f32_ubyte3_e32 v133, v109
	v_cvt_f32_ubyte2_e32 v132, v109
	v_pk_mul_f32 v[108:109], v[132:133], s[10:11] op_sel_hi:[1,0]
	v_lshlrev_b32_e32 v132, 16, v151
	v_and_b32_e32 v133, 0xffff0000, v151
	v_pk_fma_f32 v[10:11], v[10:11], v[108:109], v[132:133]
	v_cvt_f32_ubyte1_e32 v109, v110
	v_cvt_f32_ubyte0_e32 v108, v110
	v_pk_mul_f32 v[108:109], v[108:109], s[10:11] op_sel_hi:[1,0]
	s_waitcnt vmcnt(0)
; __device__ __forceinline__ unsigned cvt_pk_bf16(float lo, float hi) { unsigned r; asm volatile("v_cvt_pk_bf16_f32 %0, %1, %2" : "=v"(r) : "v"(lo), "v"(hi)); return r; }
; __device__ __forceinline__ float bf_lo(unsigned w) { return __uint_as_float(w << 16); }
; __device__ __forceinline__ float bf_hi(unsigned w) { return __uint_as_float(w & 0xffff0000u); }
;     __device__ static __forceinline__ float ub(unsigned w, int k) { return (float)((w >> (8 * k)) & 0xffu); }
;     __device__ __forceinline__ void operator()(f32x4 (&acc)[2][2][4][2], const Unit& u, int wr, int wc, int fr, int fq) const {
;     ...
;                     for (int bj = 0; bj < 2; ++bj) { const u32x4 gq = gw[ai][m]; u32x2 g; g.x = bj ? gq.z : gq.x; g.y = bj ? gq.w : gq.y; const u32x4 o = ow[m][bj]; f32x4& a0 = acc[ai][bj][m][0]; f32x4& a1 = acc[ai][bj][m][1];
;                         a0[0] = a0[0] * (ub(g.x, 0) * q) + bf_lo(o.x); a0[1] = a0[1] * (ub(g.x, 1) * q) + bf_hi(o.x); a0[2] = a0[2] * (ub(g.x, 2) * q) + bf_lo(o.y); a0[3] = a0[3] * (ub(g.x, 3) * q) + bf_hi(o.y);
;                         a1[0] = a1[0] * (ub(g.y, 0) * q) + bf_lo(o.z); a1[1] = a1[1] * (ub(g.y, 1) * q) + bf_hi(o.z); a1[2] = a1[2] * (ub(g.y, 2) * q) + bf_lo(o.w); a1[3] = a1[3] * (ub(g.y, 3) * q) + bf_hi(o.w);
;                         asm volatile("" : "+v"(a0), "+v"(a1)); }
;     ...
; #pragma unroll
;         for (int ai = 0; ai < 2; ++ai)
; #pragma unroll
;             for (int m = 0; m < 4; ++m)
; #pragma unroll
;                 for (int bj = 0; bj < 2; ++bj) { const f32x4 a0 = acc[ai][bj][m][0], a1 = acc[ai][bj][m][1];
;                     u32x4 w; w.x = cvt_pk_bf16(a0[0], a0[1]); w.y = cvt_pk_bf16(a0[2], a0[3]); w.z = cvt_pk_bf16(a1[0], a1[1]); w.w = cvt_pk_bf16(a1[2], a1[3]);
;                     *(u32x4*)mg_at(u, ai, m, bj, wr, wc, fr, fq) = w; }
	v_lshlrev_b32_e32 v132, 16, v144
	v_and_b32_e32 v133, 0xffff0000, v144
	v_pk_fma_f32 v[4:5], v[4:5], v[108:109], v[132:133]
	v_cvt_f32_ubyte3_e32 v109, v110
	v_cvt_f32_ubyte2_e32 v108, v110
	v_pk_mul_f32 v[108:109], v[108:109], s[10:11] op_sel_hi:[1,0]
	v_lshlrev_b32_e32 v132, 16, v145
	v_and_b32_e32 v133, 0xffff0000, v145
	v_pk_fma_f32 v[6:7], v[6:7], v[108:109], v[132:133]
	v_cvt_f32_ubyte1_e32 v109, v111
	v_cvt_f32_ubyte0_e32 v108, v111
	v_pk_mul_f32 v[108:109], v[108:109], s[10:11] op_sel_hi:[1,0]
	v_lshlrev_b32_e32 v132, 16, v146
	v_and_b32_e32 v133, 0xffff0000, v146
	v_pk_fma_f32 v[0:1], v[0:1], v[108:109], v[132:133]
	v_cvt_f32_ubyte3_e32 v109, v111
	v_cvt_f32_ubyte2_e32 v108, v111
	v_pk_mul_f32 v[108:109], v[108:109], s[10:11] op_sel_hi:[1,0]
	v_lshlrev_b32_e32 v110, 16, v147
	v_and_b32_e32 v111, 0xffff0000, v147
	v_pk_fma_f32 v[2:3], v[2:3], v[108:109], v[110:111]
	s_nop 0
	v_cvt_pk_bf16_f32 v108, v128, v129
	v_cvt_pk_bf16_f32 v109, v130, v131
	v_cvt_pk_bf16_f32 v110, v124, v125
	v_lshl_add_u64 v[124:125], s[64:65], 0, v[176:177]
	v_cvt_pk_bf16_f32 v111, v126, v127
	global_store_dwordx4 v[124:125], v[108:111], off sc1
	s_nop 1
	v_cvt_pk_bf16_f32 v108, v120, v121
	v_cvt_pk_bf16_f32 v109, v122, v123
	v_cvt_pk_bf16_f32 v110, v116, v117
	v_lshl_add_u64 v[116:117], s[62:63], 0, v[176:177]
	v_cvt_pk_bf16_f32 v111, v118, v119
	global_store_dwordx4 v[116:117], v[108:111], off sc1
	s_nop 1
	v_cvt_pk_bf16_f32 v108, v112, v113
	v_cvt_pk_bf16_f32 v109, v114, v115
	v_cvt_pk_bf16_f32 v110, v104, v105
	v_lshl_add_u64 v[104:105], s[64:65], 0, v[178:179]
	v_cvt_pk_bf16_f32 v111, v106, v107
	global_store_dwordx4 v[104:105], v[108:111], off sc1
	v_cvt_pk_bf16_f32 v100, v100, v101
	v_cvt_pk_bf16_f32 v101, v102, v103
	v_cvt_pk_bf16_f32 v102, v96, v97
	v_lshl_add_u64 v[96:97], s[62:63], 0, v[178:179]
	v_cvt_pk_bf16_f32 v103, v98, v99
	global_store_dwordx4 v[96:97], v[100:103], off sc1
	v_cvt_pk_bf16_f32 v92, v92, v93
	v_cvt_pk_bf16_f32 v93, v94, v95
	v_cvt_pk_bf16_f32 v94, v88, v89
	v_lshl_add_u64 v[88:89], s[64:65], 0, v[180:181]
	v_cvt_pk_bf16_f32 v95, v90, v91
	global_store_dwordx4 v[88:89], v[92:95], off sc1
	v_cvt_pk_bf16_f32 v84, v84, v85
	v_cvt_pk_bf16_f32 v85, v86, v87
	v_cvt_pk_bf16_f32 v86, v80, v81
	v_lshl_add_u64 v[80:81], s[62:63], 0, v[180:181]
	v_cvt_pk_bf16_f32 v87, v82, v83
	global_store_dwordx4 v[80:81], v[84:87], off sc1
	v_cvt_pk_bf16_f32 v76, v76, v77
	v_cvt_pk_bf16_f32 v77, v78, v79
	v_cvt_pk_bf16_f32 v78, v72, v73
	v_lshl_add_u64 v[72:73], s[64:65], 0, v[182:183]
	v_cvt_pk_bf16_f32 v79, v74, v75
	global_store_dwordx4 v[72:73], v[76:79], off sc1
	v_cvt_pk_bf16_f32 v68, v68, v69
	v_cvt_pk_bf16_f32 v69, v70, v71
	v_cvt_pk_bf16_f32 v70, v64, v65
	v_lshl_add_u64 v[64:65], s[62:63], 0, v[182:183]
	s_add_u32 s62, s6, s68
	s_addc_u32 s63, s7, s69
	s_add_u32 s64, s6, s66
	v_cvt_pk_bf16_f32 v71, v66, v67
	global_store_dwordx4 v[64:65], v[68:71], off sc1
	v_cvt_pk_bf16_f32 v60, v60, v61
	v_cvt_pk_bf16_f32 v61, v62, v63
	v_cvt_pk_bf16_f32 v62, v56, v57
	v_lshl_add_u64 v[56:57], s[62:63], 0, v[176:177]
	s_addc_u32 s65, s7, s67
	v_cvt_pk_bf16_f32 v63, v58, v59
	global_store_dwordx4 v[56:57], v[60:63], off sc1
	v_cvt_pk_bf16_f32 v52, v52, v53
	v_cvt_pk_bf16_f32 v53, v54, v55
	v_cvt_pk_bf16_f32 v54, v48, v49
	v_lshl_add_u64 v[48:49], s[64:65], 0, v[176:177]
	v_cvt_pk_bf16_f32 v55, v50, v51
	global_store_dwordx4 v[48:49], v[52:55], off sc1
	v_cvt_pk_bf16_f32 v44, v44, v45
	v_cvt_pk_bf16_f32 v45, v46, v47
	v_cvt_pk_bf16_f32 v46, v40, v41
	v_lshl_add_u64 v[40:41], s[62:63], 0, v[178:179]
	v_cvt_pk_bf16_f32 v47, v42, v43
	global_store_dwordx4 v[40:41], v[44:47], off sc1
	v_cvt_pk_bf16_f32 v36, v36, v37
	v_cvt_pk_bf16_f32 v37, v38, v39
	v_cvt_pk_bf16_f32 v38, v32, v33
	v_lshl_add_u64 v[32:33], s[64:65], 0, v[178:179]
	v_cvt_pk_bf16_f32 v39, v34, v35
	global_store_dwordx4 v[32:33], v[36:39], off sc1
	v_cvt_pk_bf16_f32 v28, v28, v29
	v_cvt_pk_bf16_f32 v29, v30, v31
	v_cvt_pk_bf16_f32 v30, v24, v25
	v_lshl_add_u64 v[24:25], s[62:63], 0, v[180:181]
	v_cvt_pk_bf16_f32 v31, v26, v27
	global_store_dwordx4 v[24:25], v[28:31], off sc1
	v_cvt_pk_bf16_f32 v20, v20, v21
	v_cvt_pk_bf16_f32 v21, v22, v23
	v_cvt_pk_bf16_f32 v22, v16, v17
	v_lshl_add_u64 v[16:17], s[64:65], 0, v[180:181]
	v_cvt_pk_bf16_f32 v23, v18, v19
	global_store_dwordx4 v[16:17], v[20:23], off sc1
	v_cvt_pk_bf16_f32 v12, v12, v13
	v_cvt_pk_bf16_f32 v13, v14, v15
	v_cvt_pk_bf16_f32 v14, v8, v9
	v_lshl_add_u64 v[8:9], s[62:63], 0, v[182:183]
	v_cvt_pk_bf16_f32 v15, v10, v11
	global_store_dwordx4 v[8:9], v[12:15], off sc1
	v_cvt_pk_bf16_f32 v4, v4, v5
	v_cvt_pk_bf16_f32 v5, v6, v7
	v_cvt_pk_bf16_f32 v6, v0, v1
	v_lshl_add_u64 v[0:1], s[64:65], 0, v[182:183]
	s_andn2_b64 vcc, exec, s[2:3]
	s_mov_b64 s[2:3], -1
	v_cvt_pk_bf16_f32 v7, v2, v3
	global_store_dwordx4 v[0:1], v[4:7], off sc1
	s_cbranch_vccnz .LBB0_662
	s_andn2_b64 vcc, exec, s[48:49]
	s_cbranch_vccnz .LBB0_661
	s_branch .LBB0_661

; #define PG8_BAR __builtin_amdgcn_s_barrier()
;     __device__ __forceinline__ char* hb_at(const Unit& u, int ai, int m, int bj, int wr, int wc, int fr, int fq) const {
;         return (char*)hb + ((size_t)((u.pm * 16 + u.pn * 4 + bj * 2 + (wc >> 1)) * 2 + ai) * HTB) + lds_byte(wr * 64 + m * 16 + fr, (wc & 1) * 32 + 8 * fq); }
;     __device__ __forceinline__ void operator()(f32x4 (&acc)[2][2][4][2], const Unit& u, int wr, int wc, int fr, int fq) const {
;         const int row0 = u.pm * BM + wr * 64 + fr, col0 = u.pn * BM + wc * 32 + 8 * fq;
;         u32x4 pre[2][4][2];
; #pragma unroll
;         for (int ai = 0; ai < 2; ++ai)
; #pragma unroll
;             for (int m = 0; m < 4; ++m)
; #pragma unroll
;                 for (int bj = 0; bj < 2; ++bj) pre[ai][m][bj] = *(const u32x4*)hb_at(u, ai, m, bj, wr, wc, fr, fq);
; template <class Epi, class Sched, bool ALIGN_EPI = false, bool SP2 = false>
; __device__ __forceinline__ void gemm_phase(PG8_LAS unsigned char* lds, const Gemm g, const Sched& S, const Epi& E) {
;     ...
;         if constexpr (ALIGN_EPI) { if (wr == 0) PG8_BAR; }
.LBB0_754:
	s_lshl_b32 s57, s66, 3
	s_lshl_b32 s59, s64, 5
	s_add_i32 s59, s59, s57
	s_or_b32 s66, s59, s77
	s_ashr_i32 s67, s66, 31
	s_lshl_b64 s[68:69], s[66:67], 14
	s_or_b32 s70, s66, 4
	v_lshl_add_u64 v[128:129], v[198:199], 0, s[68:69]
	s_ashr_i32 s71, s70, 31
	global_load_dwordx4 v[220:223], v[128:129], off
	s_lshl_b64 s[70:71], s[70:71], 14
	v_lshl_add_u64 v[128:129], v[198:199], 0, s[70:71]
	global_load_dwordx4 v[224:227], v[128:129], off
	v_lshl_add_u32 v208, s64, 8, v210
	s_or_b32 s64, s66, 1
	s_or_b32 s72, s66, 5
	s_ashr_i32 s65, s64, 31
	s_ashr_i32 s73, s72, 31
	s_lshl_b64 s[66:67], s[64:65], 14
	s_lshl_b64 s[64:65], s[72:73], 14
	v_lshl_add_u64 v[128:129], v[200:201], 0, s[68:69]
	v_lshl_add_u64 v[130:131], v[202:203], 0, s[68:69]
	v_lshl_add_u64 v[132:133], v[196:197], 0, s[68:69]
	v_lshl_add_u64 v[134:135], v[200:201], 0, s[70:71]
	v_lshl_add_u64 v[136:137], v[202:203], 0, s[70:71]
	v_lshl_add_u64 v[138:139], v[196:197], 0, s[70:71]
	v_lshl_add_u64 v[140:141], v[198:199], 0, s[66:67]
	v_lshl_add_u64 v[142:143], v[198:199], 0, s[64:65]
	v_lshl_add_u64 v[144:145], v[200:201], 0, s[66:67]
	v_lshl_add_u64 v[146:147], v[200:201], 0, s[64:65]
	v_lshl_add_u64 v[228:229], v[202:203], 0, s[66:67]
	v_lshl_add_u64 v[230:231], v[202:203], 0, s[64:65]
	v_lshl_add_u64 v[232:233], v[196:197], 0, s[66:67]
	v_lshl_add_u64 v[234:235], v[196:197], 0, s[64:65]
	global_load_dwordx4 v[180:183], v[128:129], off
	global_load_dwordx4 v[176:179], v[134:135], off
	global_load_dwordx4 v[172:175], v[130:131], off
	global_load_dwordx4 v[168:171], v[136:137], off
	global_load_dwordx4 v[164:167], v[132:133], off
	global_load_dwordx4 v[160:163], v[138:139], off
	global_load_dwordx4 v[156:159], v[140:141], off
	global_load_dwordx4 v[152:155], v[142:143], off
	global_load_dwordx4 v[148:151], v[144:145], off
	s_nop 0
	global_load_dwordx4 v[144:147], v[146:147], off
	s_nop 0
	global_load_dwordx4 v[140:143], v[228:229], off
	global_load_dwordx4 v[136:139], v[230:231], off
	global_load_dwordx4 v[132:135], v[232:233], off
	global_load_dwordx4 v[128:131], v[234:235], off
	s_add_u32 s68, s12, s68
	s_addc_u32 s69, s13, s69
	v_lshl_add_u64 v[228:229], s[68:69], 0, v[186:187]
	s_add_u32 s70, s12, s70
	s_addc_u32 s71, s13, s71
	s_cmp_lg_u64 s[4:5], 0
	s_cbranch_scc1 .Lnoal_5
	v_readlane_b32 s99, v246, 6
	s_nop 1
	s_cmp_lt_u32 s99, 4
	s_cbranch_scc0 .Lnoal_5
	s_barrier

; #define PG8_BAR __builtin_amdgcn_s_barrier()
; template <class Epi, class Sched, bool ALIGN_EPI = false, bool SP2 = false>
; __device__ __forceinline__ void gemm_phase(PG8_LAS unsigned char* lds, const Gemm g, const Sched& S, const Epi& E) {
;     ...
;         if (!has_next) break;
; #pragma unroll
;         for (int a = 0; a < 2; ++a)
; #pragma unroll
;             for (int b = 0; b < 2; ++b)
; #pragma unroll
;                 for (int m = 0; m < 4; ++m)
; #pragma unroll
;                     for (int n = 0; n < 2; ++n) acc[a][b][m][n] = (f32x4){0.f, 0.f, 0.f, 0.f};
;         cur = nxt; cA = nA; cB = nB; ++ui;
;         if constexpr (ALIGN_EPI) { if (wr == 1) PG8_BAR; }
.LBB0_770:
	s_or_b64 exec, exec, s[64:65]
	s_andn2_b64 vcc, exec, s[4:5]
	s_mov_b64 s[4:5], -1
	s_cbranch_vccnz .LBB0_743
	s_andn2_b64 vcc, exec, s[46:47]
	s_cbranch_vccnz .LBB0_742
	s_branch .LBB0_742

;     __device__ __forceinline__ void operator()(f32x4 (&acc)[2][2][4][2], const Unit& u, int wr, int wc, int fr, int fq) const {
;         const int row0 = u.pm * BM + wr * 64 + fr, col0 = u.pn * HALF + wc * 32 + 8 * fq;
;         bf16_t* Ob = O + ((size_t)(u.pm * ldc + (col0 >> 6)) * BM) * 64;
;         float sq[2][4];
; #pragma unroll
;         for (int ai = 0; ai < 2; ++ai)
; #pragma unroll
;             for (int m = 0; m < 4; ++m) sq[ai][m] = ssq[row0 + ai * HALF + m * 16];
; #pragma unroll
;         for (int ai = 0; ai < 2; ++ai)
; #pragma unroll
;             for (int m = 0; m < 4; ++m) { const float ms = sq[ai][m] * (1.0f / 1024.0f) + 1e-6f, nrl = -__builtin_amdgcn_rsqf(ms) * LOG2E;
;                 float o[8];
; #pragma unroll
;                 for (int n = 0; n < 2; ++n)
; #pragma unroll
;                     for (int e = 0; e < 4; ++e) { const float a = acc[ai][0][m][n][e], bb = acc[ai][1][m][n][e];
;                         o[4 * n + e] = (a * bb) * __builtin_amdgcn_rcpf(__builtin_fmaf(__builtin_amdgcn_exp2f(a * nrl), ms, ms)); }
.LBB0_841:
	v_lshl_add_u32 v148, s60, 8, v140
	v_ashrrev_i32_e32 v149, 31, v148
	v_lshl_add_u64 v[148:149], v[148:149], 2, s[0:1]
	global_load_dword v147, v[148:149], off
	global_load_dword v150, v[148:149], off offset:64
	global_load_dword v154, v[148:149], off offset:128
	global_load_dword v155, v[148:149], off offset:192
	global_load_dword v156, v[148:149], off offset:512
	global_load_dword v157, v[148:149], off offset:576
	global_load_dword v158, v[148:149], off offset:640
	global_load_dword v176, v[148:149], off offset:704
	s_lshl_b32 s53, s61, 7
	s_or_b32 s53, s53, s71
	s_mul_i32 s55, s60, 44
	s_ashr_i32 s53, s53, 6
	s_add_i32 s60, s53, s55
	s_ashr_i32 s61, s60, 31
	s_lshl_b64 s[60:61], s[60:61], 15
	s_add_u32 s60, s28, s60
	s_addc_u32 s61, s29, s61
	v_pk_mul_f32 v[124:125], v[116:117], v[124:125]
	v_pk_mul_f32 v[126:127], v[118:119], v[126:127]
	v_pk_mul_f32 v[120:121], v[112:113], v[120:121]
	v_pk_mul_f32 v[122:123], v[114:115], v[122:123]
	v_pk_mul_f32 v[104:105], v[108:109], v[104:105]
	v_pk_mul_f32 v[106:107], v[110:111], v[106:107]
	v_pk_mul_f32 v[96:97], v[100:101], v[96:97]
	v_pk_mul_f32 v[98:99], v[102:103], v[98:99]
	v_pk_mul_f32 v[88:89], v[92:93], v[88:89]
	v_pk_mul_f32 v[90:91], v[94:95], v[90:91]
	v_pk_mul_f32 v[80:81], v[84:85], v[80:81]
	v_pk_mul_f32 v[82:83], v[86:87], v[82:83]
	v_pk_mul_f32 v[72:73], v[76:77], v[72:73]
	v_pk_mul_f32 v[74:75], v[78:79], v[74:75]
	v_pk_mul_f32 v[64:65], v[68:69], v[64:65]
	v_pk_mul_f32 v[66:67], v[70:71], v[66:67]
	v_pk_mul_f32 v[56:57], v[60:61], v[56:57]
	v_pk_mul_f32 v[58:59], v[62:63], v[58:59]
	v_pk_mul_f32 v[48:49], v[52:53], v[48:49]
	v_pk_mul_f32 v[50:51], v[54:55], v[50:51]
	v_pk_mul_f32 v[40:41], v[44:45], v[40:41]
	v_pk_mul_f32 v[42:43], v[46:47], v[42:43]
	v_pk_mul_f32 v[32:33], v[36:37], v[32:33]
	v_pk_mul_f32 v[34:35], v[38:39], v[34:35]
	v_pk_mul_f32 v[24:25], v[28:29], v[24:25]
	v_pk_mul_f32 v[26:27], v[30:31], v[26:27]
	v_pk_mul_f32 v[16:17], v[20:21], v[16:17]
	v_pk_mul_f32 v[18:19], v[22:23], v[18:19]
	v_pk_mul_f32 v[8:9], v[12:13], v[8:9]
	v_pk_mul_f32 v[10:11], v[14:15], v[10:11]
	v_pk_mul_f32 v[0:1], v[4:5], v[0:1]
	v_pk_mul_f32 v[2:3], v[6:7], v[2:3]
	s_cmp_lg_u64 s[2:3], 0
	s_cbranch_scc1 .Lnoal_6
	v_readlane_b32 s99, v246, 6
	s_nop 1
	s_cmp_lt_u32 s99, 4
	s_cbranch_scc0 .Lnoal_6
	s_barrier
.Lnoal_6:
	s_waitcnt vmcnt(0)
	v_fmamk_f32 v152, v147, 0x3a800000, v146
	v_fmamk_f32 v160, v150, 0x3a800000, v146
	v_fmamk_f32 v162, v154, 0x3a800000, v146
	v_fmamk_f32 v164, v155, 0x3a800000, v146
	v_fmamk_f32 v166, v156, 0x3a800000, v146
	v_fmamk_f32 v168, v157, 0x3a800000, v146
	v_fmamk_f32 v170, v158, 0x3a800000, v146
	v_fmamk_f32 v172, v176, 0x3a800000, v146
	v_rsq_f32_e32 v153, v152
	v_rsq_f32_e32 v161, v160
	v_rsq_f32_e32 v163, v162
	v_rsq_f32_e32 v165, v164
	v_rsq_f32_e32 v167, v166
	v_rsq_f32_e32 v169, v168
	v_rsq_f32_e32 v171, v170
	v_rsq_f32_e32 v173, v172
	v_mul_f32_e32 v153, 0xbfb8aa3b, v153
	v_mul_f32_e32 v161, 0xbfb8aa3b, v161
	v_mul_f32_e32 v163, 0xbfb8aa3b, v163
	v_mul_f32_e32 v165, 0xbfb8aa3b, v165
	v_mul_f32_e32 v167, 0xbfb8aa3b, v167
	v_mul_f32_e32 v169, 0xbfb8aa3b, v169
	v_mul_f32_e32 v171, 0xbfb8aa3b, v171
	v_mul_f32_e32 v173, 0xbfb8aa3b, v173
	v_pk_mul_f32 v[116:117], v[116:117], v[152:153] op_sel:[0,1] op_sel_hi:[1,1]
	v_pk_mul_f32 v[118:119], v[118:119], v[152:153] op_sel:[0,1] op_sel_hi:[1,1]
	v_pk_mul_f32 v[112:113], v[112:113], v[152:153] op_sel:[0,1] op_sel_hi:[1,1]
	v_pk_mul_f32 v[114:115], v[114:115], v[152:153] op_sel:[0,1] op_sel_hi:[1,1]
	v_exp_f32_e32 v116, v116
	v_exp_f32_e32 v117, v117
	v_exp_f32_e32 v118, v118
	v_exp_f32_e32 v119, v119
	v_exp_f32_e32 v112, v112
	v_exp_f32_e32 v113, v113
	v_exp_f32_e32 v114, v114
	v_exp_f32_e32 v115, v115
	v_pk_fma_f32 v[116:117], v[116:117], v[152:153], v[152:153] op_sel_hi:[1,0,0]
	v_pk_fma_f32 v[118:119], v[118:119], v[152:153], v[152:153] op_sel_hi:[1,0,0]
	v_pk_fma_f32 v[112:113], v[112:113], v[152:153], v[152:153] op_sel_hi:[1,0,0]
	v_pk_fma_f32 v[114:115], v[114:115], v[152:153], v[152:153] op_sel_hi:[1,0,0]
	v_rcp_f32_e32 v116, v116
	v_rcp_f32_e32 v117, v117
	v_rcp_f32_e32 v118, v118
	v_rcp_f32_e32 v119, v119
	v_rcp_f32_e32 v112, v112
	v_rcp_f32_e32 v113, v113
	v_rcp_f32_e32 v114, v114
	v_rcp_f32_e32 v115, v115
	v_pk_mul_f32 v[124:125], v[124:125], v[116:117]
	v_pk_mul_f32 v[126:127], v[126:127], v[118:119]
	v_pk_mul_f32 v[120:121], v[120:121], v[112:113]
	v_pk_mul_f32 v[122:123], v[122:123], v[114:115]
	v_cvt_pk_bf16_f32 v208, v124, v125
	v_cvt_pk_bf16_f32 v209, v126, v127
	v_cvt_pk_bf16_f32 v210, v120, v121
	v_cvt_pk_bf16_f32 v211, v122, v123
	v_lshl_add_u64 v[174:175], s[60:61], 0, v[128:129]
	global_store_dwordx4 v[174:175], v[208:211], off sc1
	v_pk_mul_f32 v[108:109], v[108:109], v[160:161] op_sel:[0,1] op_sel_hi:[1,1]
	v_pk_mul_f32 v[110:111], v[110:111], v[160:161] op_sel:[0,1] op_sel_hi:[1,1]
	v_pk_mul_f32 v[100:101], v[100:101], v[160:161] op_sel:[0,1] op_sel_hi:[1,1]
	v_pk_mul_f32 v[102:103], v[102:103], v[160:161] op_sel:[0,1] op_sel_hi:[1,1]
	v_exp_f32_e32 v108, v108
	v_exp_f32_e32 v109, v109
	v_exp_f32_e32 v110, v110
	v_exp_f32_e32 v111, v111
	v_exp_f32_e32 v100, v100
	v_exp_f32_e32 v101, v101
	v_exp_f32_e32 v102, v102
	v_exp_f32_e32 v103, v103
	v_pk_fma_f32 v[108:109], v[108:109], v[160:161], v[160:161] op_sel_hi:[1,0,0]
	v_pk_fma_f32 v[110:111], v[110:111], v[160:161], v[160:161] op_sel_hi:[1,0,0]
	v_pk_fma_f32 v[100:101], v[100:101], v[160:161], v[160:161] op_sel_hi:[1,0,0]
	v_pk_fma_f32 v[102:103], v[102:103], v[160:161], v[160:161] op_sel_hi:[1,0,0]
	v_rcp_f32_e32 v108, v108
	v_rcp_f32_e32 v109, v109
	v_rcp_f32_e32 v110, v110
	v_rcp_f32_e32 v111, v111
	v_rcp_f32_e32 v100, v100
; __device__ __forceinline__ unsigned cvt_pk_bf16(float lo, float hi) { unsigned r; asm volatile("v_cvt_pk_bf16_f32 %0, %1, %2" : "=v"(r) : "v"(lo), "v"(hi)); return r; }
;     __device__ __forceinline__ void operator()(f32x4 (&acc)[2][2][4][2], const Unit& u, int wr, int wc, int fr, int fq) const {
;     ...
;             for (int m = 0; m < 4; ++m) { const float ms = sq[ai][m] * (1.0f / 1024.0f) + 1e-6f, nrl = -__builtin_amdgcn_rsqf(ms) * LOG2E;
;                 float o[8];
; #pragma unroll
;                 for (int n = 0; n < 2; ++n)
; #pragma unroll
;                     for (int e = 0; e < 4; ++e) { const float a = acc[ai][0][m][n][e], bb = acc[ai][1][m][n][e];
;                         o[4 * n + e] = (a * bb) * __builtin_amdgcn_rcpf(__builtin_fmaf(__builtin_amdgcn_exp2f(a * nrl), ms, ms)); }
;                 u32x4 w; w.x = cvt_pk_bf16(o[0], o[1]); w.y = cvt_pk_bf16(o[2], o[3]); w.z = cvt_pk_bf16(o[4], o[5]); w.w = cvt_pk_bf16(o[6], o[7]);
;                 *(u32x4*)((char*)Ob + ai * HTB + lds_byte(wr * 64 + m * 16 + fr, (col0 & 63))) = w; }
	v_rcp_f32_e32 v101, v101
	v_rcp_f32_e32 v102, v102
	v_rcp_f32_e32 v103, v103
	v_pk_mul_f32 v[104:105], v[104:105], v[108:109]
	v_pk_mul_f32 v[106:107], v[106:107], v[110:111]
	v_pk_mul_f32 v[96:97], v[96:97], v[100:101]
	v_pk_mul_f32 v[98:99], v[98:99], v[102:103]
	v_cvt_pk_bf16_f32 v212, v104, v105
	v_cvt_pk_bf16_f32 v213, v106, v107
	v_cvt_pk_bf16_f32 v214, v96, v97
	v_cvt_pk_bf16_f32 v215, v98, v99
	v_lshl_add_u64 v[174:175], s[60:61], 0, v[130:131]
	global_store_dwordx4 v[174:175], v[212:215], off sc1
	v_pk_mul_f32 v[92:93], v[92:93], v[162:163] op_sel:[0,1] op_sel_hi:[1,1]
	v_pk_mul_f32 v[94:95], v[94:95], v[162:163] op_sel:[0,1] op_sel_hi:[1,1]
	v_pk_mul_f32 v[84:85], v[84:85], v[162:163] op_sel:[0,1] op_sel_hi:[1,1]
	v_pk_mul_f32 v[86:87], v[86:87], v[162:163] op_sel:[0,1] op_sel_hi:[1,1]
	v_exp_f32_e32 v92, v92
	v_exp_f32_e32 v93, v93
	v_exp_f32_e32 v94, v94
	v_exp_f32_e32 v95, v95
	v_exp_f32_e32 v84, v84
	v_exp_f32_e32 v85, v85
	v_exp_f32_e32 v86, v86
	v_exp_f32_e32 v87, v87
	v_pk_fma_f32 v[92:93], v[92:93], v[162:163], v[162:163] op_sel_hi:[1,0,0]
	v_pk_fma_f32 v[94:95], v[94:95], v[162:163], v[162:163] op_sel_hi:[1,0,0]
	v_pk_fma_f32 v[84:85], v[84:85], v[162:163], v[162:163] op_sel_hi:[1,0,0]
	v_pk_fma_f32 v[86:87], v[86:87], v[162:163], v[162:163] op_sel_hi:[1,0,0]
	v_rcp_f32_e32 v92, v92
	v_rcp_f32_e32 v93, v93
	v_rcp_f32_e32 v94, v94
	v_rcp_f32_e32 v95, v95
	v_rcp_f32_e32 v84, v84
	v_rcp_f32_e32 v85, v85
	v_rcp_f32_e32 v86, v86
	v_rcp_f32_e32 v87, v87
	v_pk_mul_f32 v[88:89], v[88:89], v[92:93]
	v_pk_mul_f32 v[90:91], v[90:91], v[94:95]
	v_pk_mul_f32 v[80:81], v[80:81], v[84:85]
	v_pk_mul_f32 v[82:83], v[82:83], v[86:87]
	v_cvt_pk_bf16_f32 v208, v88, v89
	v_cvt_pk_bf16_f32 v209, v90, v91
	v_cvt_pk_bf16_f32 v210, v80, v81
	v_cvt_pk_bf16_f32 v211, v82, v83
	v_lshl_add_u64 v[174:175], s[60:61], 0, v[132:133]
	global_store_dwordx4 v[174:175], v[208:211], off sc1
	v_pk_mul_f32 v[76:77], v[76:77], v[164:165] op_sel:[0,1] op_sel_hi:[1,1]
	v_pk_mul_f32 v[78:79], v[78:79], v[164:165] op_sel:[0,1] op_sel_hi:[1,1]
	v_pk_mul_f32 v[68:69], v[68:69], v[164:165] op_sel:[0,1] op_sel_hi:[1,1]
	v_pk_mul_f32 v[70:71], v[70:71], v[164:165] op_sel:[0,1] op_sel_hi:[1,1]
	v_exp_f32_e32 v76, v76
	v_exp_f32_e32 v77, v77
	v_exp_f32_e32 v78, v78
	v_exp_f32_e32 v79, v79
	v_exp_f32_e32 v68, v68
	v_exp_f32_e32 v69, v69
	v_exp_f32_e32 v70, v70
	v_exp_f32_e32 v71, v71
	v_pk_fma_f32 v[76:77], v[76:77], v[164:165], v[164:165] op_sel_hi:[1,0,0]
	v_pk_fma_f32 v[78:79], v[78:79], v[164:165], v[164:165] op_sel_hi:[1,0,0]
	v_pk_fma_f32 v[68:69], v[68:69], v[164:165], v[164:165] op_sel_hi:[1,0,0]
	v_pk_fma_f32 v[70:71], v[70:71], v[164:165], v[164:165] op_sel_hi:[1,0,0]
	v_rcp_f32_e32 v76, v76
	v_rcp_f32_e32 v77, v77
	v_rcp_f32_e32 v78, v78
	v_rcp_f32_e32 v79, v79
	v_rcp_f32_e32 v68, v68
	v_rcp_f32_e32 v69, v69
	v_rcp_f32_e32 v70, v70
	v_rcp_f32_e32 v71, v71
	v_pk_mul_f32 v[72:73], v[72:73], v[76:77]
	v_pk_mul_f32 v[74:75], v[74:75], v[78:79]
	v_pk_mul_f32 v[64:65], v[64:65], v[68:69]
	v_pk_mul_f32 v[66:67], v[66:67], v[70:71]
	v_cvt_pk_bf16_f32 v212, v72, v73
	v_cvt_pk_bf16_f32 v213, v74, v75
	v_cvt_pk_bf16_f32 v214, v64, v65
	v_cvt_pk_bf16_f32 v215, v66, v67
	v_lshl_add_u64 v[174:175], s[60:61], 0, v[134:135]
	global_store_dwordx4 v[174:175], v[212:215], off sc1
	s_add_u32 s60, s60, 0x4000
	s_addc_u32 s61, s61, 0
	v_pk_mul_f32 v[60:61], v[60:61], v[166:167] op_sel:[0,1] op_sel_hi:[1,1]
	v_pk_mul_f32 v[62:63], v[62:63], v[166:167] op_sel:[0,1] op_sel_hi:[1,1]
	v_pk_mul_f32 v[52:53], v[52:53], v[166:167] op_sel:[0,1] op_sel_hi:[1,1]
	v_pk_mul_f32 v[54:55], v[54:55], v[166:167] op_sel:[0,1] op_sel_hi:[1,1]
	v_exp_f32_e32 v60, v60
	v_exp_f32_e32 v61, v61
	v_exp_f32_e32 v62, v62
	v_exp_f32_e32 v63, v63
	v_exp_f32_e32 v52, v52
	v_exp_f32_e32 v53, v53
	v_exp_f32_e32 v54, v54
	v_exp_f32_e32 v55, v55
	v_pk_fma_f32 v[60:61], v[60:61], v[166:167], v[166:167] op_sel_hi:[1,0,0]
	v_pk_fma_f32 v[62:63], v[62:63], v[166:167], v[166:167] op_sel_hi:[1,0,0]
	v_pk_fma_f32 v[52:53], v[52:53], v[166:167], v[166:167] op_sel_hi:[1,0,0]
	v_pk_fma_f32 v[54:55], v[54:55], v[166:167], v[166:167] op_sel_hi:[1,0,0]
	v_rcp_f32_e32 v60, v60
	v_rcp_f32_e32 v61, v61
	v_rcp_f32_e32 v62, v62
	v_rcp_f32_e32 v63, v63
	v_rcp_f32_e32 v52, v52
	v_rcp_f32_e32 v53, v53
	v_rcp_f32_e32 v54, v54
	v_rcp_f32_e32 v55, v55
	v_pk_mul_f32 v[56:57], v[56:57], v[60:61]
	v_pk_mul_f32 v[58:59], v[58:59], v[62:63]
	v_pk_mul_f32 v[48:49], v[48:49], v[52:53]
	v_pk_mul_f32 v[50:51], v[50:51], v[54:55]
; __device__ __forceinline__ unsigned cvt_pk_bf16(float lo, float hi) { unsigned r; asm volatile("v_cvt_pk_bf16_f32 %0, %1, %2" : "=v"(r) : "v"(lo), "v"(hi)); return r; }
;     __device__ __forceinline__ void operator()(f32x4 (&acc)[2][2][4][2], const Unit& u, int wr, int wc, int fr, int fq) const {
;     ...
;             for (int m = 0; m < 4; ++m) { const float ms = sq[ai][m] * (1.0f / 1024.0f) + 1e-6f, nrl = -__builtin_amdgcn_rsqf(ms) * LOG2E;
;                 float o[8];
; #pragma unroll
;                 for (int n = 0; n < 2; ++n)
; #pragma unroll
;                     for (int e = 0; e < 4; ++e) { const float a = acc[ai][0][m][n][e], bb = acc[ai][1][m][n][e];
;                         o[4 * n + e] = (a * bb) * __builtin_amdgcn_rcpf(__builtin_fmaf(__builtin_amdgcn_exp2f(a * nrl), ms, ms)); }
;                 u32x4 w; w.x = cvt_pk_bf16(o[0], o[1]); w.y = cvt_pk_bf16(o[2], o[3]); w.z = cvt_pk_bf16(o[4], o[5]); w.w = cvt_pk_bf16(o[6], o[7]);
;                 *(u32x4*)((char*)Ob + ai * HTB + lds_byte(wr * 64 + m * 16 + fr, (col0 & 63))) = w; }
	v_cvt_pk_bf16_f32 v208, v56, v57
	v_cvt_pk_bf16_f32 v209, v58, v59
	v_cvt_pk_bf16_f32 v210, v48, v49
	v_cvt_pk_bf16_f32 v211, v50, v51
	v_lshl_add_u64 v[174:175], s[60:61], 0, v[128:129]
	global_store_dwordx4 v[174:175], v[208:211], off sc1
	v_pk_mul_f32 v[44:45], v[44:45], v[168:169] op_sel:[0,1] op_sel_hi:[1,1]
	v_pk_mul_f32 v[46:47], v[46:47], v[168:169] op_sel:[0,1] op_sel_hi:[1,1]
	v_pk_mul_f32 v[36:37], v[36:37], v[168:169] op_sel:[0,1] op_sel_hi:[1,1]
	v_pk_mul_f32 v[38:39], v[38:39], v[168:169] op_sel:[0,1] op_sel_hi:[1,1]
	v_exp_f32_e32 v44, v44
	v_exp_f32_e32 v45, v45
	v_exp_f32_e32 v46, v46
	v_exp_f32_e32 v47, v47
	v_exp_f32_e32 v36, v36
	v_exp_f32_e32 v37, v37
	v_exp_f32_e32 v38, v38
	v_exp_f32_e32 v39, v39
	v_pk_fma_f32 v[44:45], v[44:45], v[168:169], v[168:169] op_sel_hi:[1,0,0]
	v_pk_fma_f32 v[46:47], v[46:47], v[168:169], v[168:169] op_sel_hi:[1,0,0]
	v_pk_fma_f32 v[36:37], v[36:37], v[168:169], v[168:169] op_sel_hi:[1,0,0]
	v_pk_fma_f32 v[38:39], v[38:39], v[168:169], v[168:169] op_sel_hi:[1,0,0]
	v_rcp_f32_e32 v44, v44
	v_rcp_f32_e32 v45, v45
	v_rcp_f32_e32 v46, v46
	v_rcp_f32_e32 v47, v47
	v_rcp_f32_e32 v36, v36
	v_rcp_f32_e32 v37, v37
	v_rcp_f32_e32 v38, v38
	v_rcp_f32_e32 v39, v39
	v_pk_mul_f32 v[40:41], v[40:41], v[44:45]
	v_pk_mul_f32 v[42:43], v[42:43], v[46:47]
	v_pk_mul_f32 v[32:33], v[32:33], v[36:37]
	v_pk_mul_f32 v[34:35], v[34:35], v[38:39]
	v_cvt_pk_bf16_f32 v212, v40, v41
	v_cvt_pk_bf16_f32 v213, v42, v43
	v_cvt_pk_bf16_f32 v214, v32, v33
	v_cvt_pk_bf16_f32 v215, v34, v35
	v_lshl_add_u64 v[174:175], s[60:61], 0, v[130:131]
	global_store_dwordx4 v[174:175], v[212:215], off sc1
	v_pk_mul_f32 v[28:29], v[28:29], v[170:171] op_sel:[0,1] op_sel_hi:[1,1]
	v_pk_mul_f32 v[30:31], v[30:31], v[170:171] op_sel:[0,1] op_sel_hi:[1,1]
	v_pk_mul_f32 v[20:21], v[20:21], v[170:171] op_sel:[0,1] op_sel_hi:[1,1]
	v_pk_mul_f32 v[22:23], v[22:23], v[170:171] op_sel:[0,1] op_sel_hi:[1,1]
	v_exp_f32_e32 v28, v28
	v_exp_f32_e32 v29, v29
	v_exp_f32_e32 v30, v30
	v_exp_f32_e32 v31, v31
	v_exp_f32_e32 v20, v20
	v_exp_f32_e32 v21, v21
	v_exp_f32_e32 v22, v22
	v_exp_f32_e32 v23, v23
	v_pk_fma_f32 v[28:29], v[28:29], v[170:171], v[170:171] op_sel_hi:[1,0,0]
	v_pk_fma_f32 v[30:31], v[30:31], v[170:171], v[170:171] op_sel_hi:[1,0,0]
	v_pk_fma_f32 v[20:21], v[20:21], v[170:171], v[170:171] op_sel_hi:[1,0,0]
	v_pk_fma_f32 v[22:23], v[22:23], v[170:171], v[170:171] op_sel_hi:[1,0,0]
	v_rcp_f32_e32 v28, v28
	v_rcp_f32_e32 v29, v29
	v_rcp_f32_e32 v30, v30
	v_rcp_f32_e32 v31, v31
	v_rcp_f32_e32 v20, v20
	v_rcp_f32_e32 v21, v21
	v_rcp_f32_e32 v22, v22
	v_rcp_f32_e32 v23, v23
	v_pk_mul_f32 v[24:25], v[24:25], v[28:29]
	v_pk_mul_f32 v[26:27], v[26:27], v[30:31]
	v_pk_mul_f32 v[16:17], v[16:17], v[20:21]
	v_pk_mul_f32 v[18:19], v[18:19], v[22:23]
	v_cvt_pk_bf16_f32 v208, v24, v25
	v_cvt_pk_bf16_f32 v209, v26, v27
	v_cvt_pk_bf16_f32 v210, v16, v17
	v_cvt_pk_bf16_f32 v211, v18, v19
	v_lshl_add_u64 v[174:175], s[60:61], 0, v[132:133]
	global_store_dwordx4 v[174:175], v[208:211], off sc1
	v_pk_mul_f32 v[12:13], v[12:13], v[172:173] op_sel:[0,1] op_sel_hi:[1,1]
	v_pk_mul_f32 v[14:15], v[14:15], v[172:173] op_sel:[0,1] op_sel_hi:[1,1]
	v_pk_mul_f32 v[4:5], v[4:5], v[172:173] op_sel:[0,1] op_sel_hi:[1,1]
	v_pk_mul_f32 v[6:7], v[6:7], v[172:173] op_sel:[0,1] op_sel_hi:[1,1]
	v_exp_f32_e32 v12, v12
	v_exp_f32_e32 v13, v13
	v_exp_f32_e32 v14, v14
	v_exp_f32_e32 v15, v15
	v_exp_f32_e32 v4, v4
	v_exp_f32_e32 v5, v5
	v_exp_f32_e32 v6, v6
	v_exp_f32_e32 v7, v7
	v_pk_fma_f32 v[12:13], v[12:13], v[172:173], v[172:173] op_sel_hi:[1,0,0]
	v_pk_fma_f32 v[14:15], v[14:15], v[172:173], v[172:173] op_sel_hi:[1,0,0]
	v_pk_fma_f32 v[4:5], v[4:5], v[172:173], v[172:173] op_sel_hi:[1,0,0]
	v_pk_fma_f32 v[6:7], v[6:7], v[172:173], v[172:173] op_sel_hi:[1,0,0]
	v_rcp_f32_e32 v12, v12
	v_rcp_f32_e32 v13, v13
	v_rcp_f32_e32 v14, v14
	v_rcp_f32_e32 v15, v15
	v_rcp_f32_e32 v4, v4
	v_rcp_f32_e32 v5, v5
	v_rcp_f32_e32 v6, v6
	v_rcp_f32_e32 v7, v7
	v_pk_mul_f32 v[8:9], v[8:9], v[12:13]
	v_pk_mul_f32 v[10:11], v[10:11], v[14:15]
	v_pk_mul_f32 v[0:1], v[0:1], v[4:5]
	v_pk_mul_f32 v[2:3], v[2:3], v[6:7]
	v_cvt_pk_bf16_f32 v212, v8, v9
	v_cvt_pk_bf16_f32 v213, v10, v11
	v_cvt_pk_bf16_f32 v214, v0, v1
	v_cvt_pk_bf16_f32 v215, v2, v3
	v_lshl_add_u64 v[174:175], s[60:61], 0, v[134:135]
	global_store_dwordx4 v[174:175], v[212:215], off sc1
	s_andn2_b64 vcc, exec, s[2:3]
	s_mov_b64 s[2:3], -1
	s_cbranch_vccnz .LBB0_834
	s_andn2_b64 vcc, exec, s[42:43]
	s_cbranch_vccnz .LBB0_833
	s_branch .LBB0_833
